# attention: 4-tile unrolled fast loop with static LDS ring offsets + per-lane partial softmax row-sum (halves combined once per unit)
# baseline (speedup 1.0000x reference)
; #define LAS __attribute__((address_space(3)))
; __device__ __forceinline__ int v_st(int k, int c) { const int kk = k; return ((kk >> 3) * 4 + (c >> 5)) * 512 + ((kk & 7) * 32 + (c & 31)) * 2; }
; __device__ __forceinline__ int v_rd_base(int lane) { return ((lane & 3) << 3) | (((lane >> 2) & 3) << 6) | (((lane >> 4) & 1) << 5) | (((lane >> 5) & 1) << 8); }
; #define ABAR() asm volatile("s_waitcnt lgkmcnt(0)\n\ts_barrier" ::: "memory")
; #define SLOAD(i, k0) do { const bf16_t* vt_ = Vh + (size_t)(k0) * 512; const bf16_t* kt_ = KNh + (size_t)(k0) * 512; const bf16_t* rt_ = KRb + (size_t)(k0) * 32; \
;     sr_[i].vs = *reinterpret_cast<const bf16x8*>(vt_ + lo_kv); sr_[i].ks = *reinterpret_cast<const bf16x8*>(kt_ + lo_kv); sr_[i].kr = *reinterpret_cast<const s16x4*>(rt_ + lo_kr); } while (0)
; #define SWRITE(slot, i) do { *(bf16x8*)(V_lds + (slot) * SHM_V + vst) = sr_[i].vs; *(bf16x8*)(K_lds + (slot) * SHM_K + kst) = sr_[i].ks; *(s16x4*)(K_lds + (slot) * SHM_K + krst) = sr_[i].kr; } while (0)
; __device__ __forceinline__ void attn_unit(const bf16_t* __restrict__ Qb, const bf16_t* __restrict__ KNh, const bf16_t* __restrict__ KRb, const bf16_t* __restrict__ Vh, bf16_t* __restrict__ Ob, char* lds) {
;     ...
;   float mref = 0.f, l_reg = 0; f32x16 negm = {}; f32x16 o[2] = {}; bf16x8 qr[6];
;   const bf16_t* Qw = Qb + (long)(wid * QBLK + r32) * 768 + hi * 8;
; #pragma unroll
;   for (int d0 = 0; d0 < 6; ++d0) qr[d0] = *reinterpret_cast<const bf16x8*>(Qw + d0 * 16);
;   const int sr = tid >> 3, sc = (tid & 7) * 8, vst = v_st(sr, sc), kst = KSWZ(sr, sc * 2), krst = KSWZ(sr, 128 + (tid & 7) * 8);
;   const lds_cptr vb0 = (lds_cptr)(LAS char*)lds + v_rd_base(lane);
;   struct { bf16x8 vs, ks; s16x4 kr; } sr_[2];
;   const unsigned lo_kv = (unsigned)(sr * 512 + sc), lo_kr = (unsigned)(sr * 32 + (tid & 7) * 4);
;     ...
;   if (__builtin_amdgcn_readfirstlane(tid >> 6) >= 4) __builtin_amdgcn_s_setprio(1);
;   f32x16 pA0, pA1, pB0, pB1; float alA, alB; bf16x8 pa0, pa1, pa2, pa3; constexpr int NT = SEQ / KVBLK;
;   SLOAD(0, 0); SLOAD(1, KVBLK); asm volatile("s_waitcnt vmcnt(0)" ::: "memory"); SWRITE(0, 0); SWRITE(1, 1); SLOAD(0, 2 * KVBLK); ABAR();
;   qkt(pA0, pA1, K_lds, qr, negm, r32, hi); partialSM<true>(pA0, pA1, mref, negm, alA);
;   SWRITE(2, 0); SLOAD(1, 3 * KVBLK); ABAR();
.LBB0_738:
	s_xor_b64 s[34:35], s[30:31], -1
	s_lshr_b32 s91, s33, 3
	s_lshl_b64 s[62:63], s[42:43], 21
	s_add_u32 s44, s14, s62
	s_addc_u32 s45, s15, s63
	s_lshl_b32 s88, s41, 6
	s_lshl_b32 s41, s41, 7
	s_add_u32 s44, s44, s41
	s_addc_u32 s45, s45, 0
	s_lshl_b64 s[64:65], s[42:43], 17
	s_add_u32 s42, s24, s64
	v_readlane_b32 s43, v252, 36
	s_addc_u32 s43, s43, s65
	s_add_u32 s46, s25, s62
	s_addc_u32 s47, s97, s63
	s_add_u32 s46, s46, s41
	s_addc_u32 s47, s47, 0
	v_mov_b32_e32 v169, v153
	v_lshl_add_u64 v[52:53], s[46:47], 0, v[168:169]
	s_mov_b32 s89, 0x10000
	v_add_co_u32_e32 v8, vcc, s89, v52
	v_lshl_add_u64 v[50:51], s[44:45], 0, v[168:169]
	s_nop 0
	v_addc_co_u32_e32 v9, vcc, 0, v53, vcc
	v_add_co_u32_e32 v12, vcc, s89, v50
	global_load_dwordx4 v[0:3], v168, s[46:47]
	s_nop 0
	v_addc_co_u32_e32 v13, vcc, 0, v51, vcc
	global_load_dwordx4 v[4:7], v168, s[44:45]
	global_load_dwordx2 v[16:17], v170, s[42:43]
	s_nop 0
	global_load_dwordx4 v[8:11], v[8:9], off
	s_nop 0
	global_load_dwordx4 v[12:15], v[12:13], off
	v_mov_b32_e32 v171, v153
	v_lshl_add_u64 v[48:49], s[42:43], 0, v[170:171]
	v_add_co_u32_e32 v18, vcc, s70, v48
	v_add_u32_e32 v26, s85, v201
	s_nop 0
	v_addc_co_u32_e32 v19, vcc, 0, v49, vcc
	global_load_dwordx2 v[20:21], v[18:19], off offset:-4096
	v_add_co_u32_e32 v22, vcc, s67, v50
	s_waitcnt vmcnt(0)
	v_add_u32_e32 v27, s85, v202
	s_nop 0
	v_addc_co_u32_e32 v23, vcc, 0, v51, vcc
	v_add_co_u32_e32 v24, vcc, s67, v52
	v_add_u32_e32 v28, s82, v201
	s_nop 0
	v_addc_co_u32_e32 v25, vcc, 0, v53, vcc
	v_add_u32_e32 v29, s82, v202
	global_load_dwordx4 v[136:139], v[24:25], off
	global_load_dwordx4 v[140:143], v[22:23], off
	global_load_dwordx2 v[172:173], v[18:19], off
	v_add_u32_e32 v30, s85, v206
	v_add_co_u32_e32 v62, vcc, s84, v52
	v_add_u32_e32 v64, s85, v211
	s_nop 0
	v_addc_co_u32_e32 v63, vcc, 0, v53, vcc
	s_mov_b32 s41, s40
	s_mov_b32 s42, s40
	s_mov_b32 s43, s40
	s_mov_b32 s44, s40
	s_mov_b32 s45, s40
	s_mov_b32 s46, s40
	s_mov_b32 s47, s40
	s_mov_b32 s48, s40
	s_mov_b32 s49, s40
	s_mov_b32 s50, s40
	s_mov_b32 s51, s40
	s_mov_b32 s52, s40
	s_mov_b32 s53, s40
	s_mov_b32 s54, s40
	s_mov_b32 s55, s40
	s_mov_b32 s90, 1
	v_mov_b32_e32 v177, s65
	v_or_b32_e32 v176, s64, v154
	v_mov_b32_e32 v152, 0
	v_mov_b32_e32 v163, 1.0
	s_waitcnt vmcnt(7)
	ds_write_b128 v26, v[4:7]
	s_waitcnt vmcnt(6)
	ds_write_b64 v27, v[16:17]
	ds_write_b128 v204, v[0:3]
	s_waitcnt vmcnt(5)
	ds_write_b128 v204, v[8:11] offset:16384
	s_waitcnt vmcnt(4)
	ds_write_b128 v28, v[12:15]
	s_waitcnt vmcnt(3)
	ds_write_b64 v29, v[20:21]
	s_waitcnt lgkmcnt(0)
	s_barrier
	ds_read_b128 v[0:3], v30
	ds_read_b128 v[4:7], v30 offset:8192
	s_waitcnt lgkmcnt(1)
	v_mfma_f32_32x32x16_bf16 v[32:47], v[0:3], v[132:135], 0
	v_add_u32_e32 v8, s85, v207
	s_waitcnt lgkmcnt(0)
	v_mfma_f32_32x32x16_bf16 v[16:31], v[4:7], v[132:135], 0
	ds_read_b128 v[0:3], v8
	ds_read_b128 v[4:7], v8 offset:8192
	v_add_u32_e32 v8, s85, v208
	s_waitcnt lgkmcnt(1)
	v_mfma_f32_32x32x16_bf16 v[32:47], v[0:3], v[128:131], v[32:47]
	s_waitcnt lgkmcnt(0)
	v_mfma_f32_32x32x16_bf16 v[16:31], v[4:7], v[128:131], v[16:31]
	ds_read_b128 v[0:3], v8
	ds_read_b128 v[4:7], v8 offset:8192
	v_add_u32_e32 v8, s85, v209
	ds_read_b128 v[58:61], v64
	s_waitcnt lgkmcnt(2)
	v_mfma_f32_32x32x16_bf16 v[32:47], v[0:3], v[124:127], v[32:47]
	ds_read_b128 v[0:3], v8
	s_waitcnt lgkmcnt(2)
	v_mfma_f32_32x32x16_bf16 v[16:31], v[4:7], v[124:127], v[16:31]
	ds_read_b128 v[4:7], v8 offset:8192
	v_add_u32_e32 v8, s85, v210
	ds_read_b128 v[54:57], v8 offset:8192
	s_waitcnt lgkmcnt(2)
	v_mfma_f32_32x32x16_bf16 v[32:47], v[0:3], v[120:123], v[32:47]
	ds_read_b128 v[0:3], v8
	s_waitcnt lgkmcnt(2)
	v_mfma_f32_32x32x16_bf16 v[16:31], v[4:7], v[120:123], v[16:31]
	s_waitcnt lgkmcnt(1)
	v_mfma_f32_32x32x16_bf16 v[16:31], v[54:57], v[116:119], v[16:31]
	v_add_co_u32_e32 v54, vcc, s84, v50
	s_nop 1
	v_addc_co_u32_e32 v55, vcc, 0, v51, vcc
	v_add_co_u32_e32 v48, vcc, s80, v48
	ds_read_b128 v[50:53], v64 offset:8192
	s_nop 0
	v_addc_co_u32_e32 v49, vcc, 0, v49, vcc
	global_load_dwordx4 v[144:147], v[62:63], off
	global_load_dwordx4 v[148:151], v[54:55], off
	global_load_dwordx2 v[174:175], v[48:49], off
	s_waitcnt lgkmcnt(1)
	v_mfma_f32_32x32x16_bf16 v[32:47], v[0:3], v[116:119], v[32:47]
	v_mov_b64_e32 v[0:1], s[40:41]
	v_mov_b64_e32 v[2:3], s[42:43]
	v_mov_b64_e32 v[4:5], s[44:45]
	v_mov_b64_e32 v[6:7], s[46:47]
	v_mov_b64_e32 v[8:9], s[48:49]
	v_mov_b64_e32 v[10:11], s[50:51]
	v_mov_b64_e32 v[12:13], s[52:53]
	v_mfma_f32_32x32x16_bf16 v[32:47], v[58:61], v[112:115], v[32:47]
	v_mov_b64_e32 v[14:15], s[54:55]
	s_and_b32 s41, s91, 7
	s_waitcnt vmcnt(5)
	ds_write_b128 v204, v[136:139] offset:32768
	s_lshl_b32 s41, s41, 7
	s_or_b32 s62, s62, s41
	v_lshl_add_u64 v[178:179], s[62:63], 0, v[158:159]
	s_add_u32 s98, s22, s62
	s_addc_u32 s99, s23, s63
	s_add_u32 s98, s98, 0x40000
	s_addc_u32 s99, s99, 0
	s_add_u32 s100, s22, s64
	s_addc_u32 s101, s23, s65
	s_add_u32 s100, s100, 0x4000
	s_addc_u32 s101, s101, 0
	v_add_u32_e32 v240, 0x2a800000, v158
	v_add_u32_e32 v241, 0x26800000, v158
	v_add_u32_e32 v242, 0x2e800000, v154
	v_add_u32_e32 v243, 0x10000, v206
	v_add_u32_e32 v244, 0x10000, v207
	v_add_u32_e32 v245, 0x10000, v208
	v_add_u32_e32 v246, 0x10000, v209
	v_add_u32_e32 v247, 0x10000, v210
	v_add_u32_e32 v248, 0x10000, v211
	v_add_u32_e32 v249, 0x10000, v201
	v_add_u32_e32 v250, 0x10000, v202
	s_nop 4
	v_max_f32_e32 v48, v33, v33
	v_max_f32_e32 v49, v32, v32
	s_waitcnt lgkmcnt(1)
; #define ABAR() asm volatile("s_waitcnt lgkmcnt(0)\n\ts_barrier" ::: "memory")
; #define SLOAD(i, k0) do { const bf16_t* vt_ = Vh + (size_t)(k0) * 512; const bf16_t* kt_ = KNh + (size_t)(k0) * 512; const bf16_t* rt_ = KRb + (size_t)(k0) * 32; \
;     sr_[i].vs = *reinterpret_cast<const bf16x8*>(vt_ + lo_kv); sr_[i].ks = *reinterpret_cast<const bf16x8*>(kt_ + lo_kv); sr_[i].kr = *reinterpret_cast<const s16x4*>(rt_ + lo_kr); } while (0)
; #define SWRITE(slot, i) do { *(bf16x8*)(V_lds + (slot) * SHM_V + vst) = sr_[i].vs; *(bf16x8*)(K_lds + (slot) * SHM_K + kst) = sr_[i].ks; *(s16x4*)(K_lds + (slot) * SHM_K + krst) = sr_[i].kr; } while (0)
; template <bool FIRST> __device__ __forceinline__ void partialSM(f32x16& p0, f32x16& p1, float& mref, f32x16& negm, float& alpha) {
;   constexpr float THRL = THR * 1.4426950408889634f;
;   float pmax = p0[0];
; #pragma unroll
;   for (int r = 1; r < 16; ++r) pmax = fmaxf(pmax, p0[r]);
; #pragma unroll
;   for (int r = 0; r < 16; ++r) pmax = fmaxf(pmax, p1[r]);
;   { auto rr = __builtin_amdgcn_permlane32_swap(__float_as_uint(pmax), __float_as_uint(pmax), false, false);
;     pmax = fmaxf(__uint_as_float(rr[0]), __uint_as_float(rr[1])); }
;   if (!FIRST && __builtin_expect(__all(pmax <= THRL), 1)) { alpha = 1.f; }
;   else { const float dl = FIRST ? pmax : fmaxf(pmax, 0.f); mref += dl; alpha = FIRST ? 1.f : __builtin_amdgcn_exp2f(-dl);
; #pragma unroll
;     for (int r = 0; r < 16; ++r) { p0[r] -= dl; p1[r] -= dl; }
;     const float nm = -mref;
; #pragma unroll
;     for (int r = 0; r < 16; ++r) negm[r] = nm; }
; #pragma unroll
;   for (int r = 0; r < 16; ++r) p0[r] = __builtin_amdgcn_exp2f(p0[r]);
; }
; __device__ __forceinline__ void attn_unit(const bf16_t* __restrict__ Qb, const bf16_t* __restrict__ KNh, const bf16_t* __restrict__ KRb, const bf16_t* __restrict__ Vh, bf16_t* __restrict__ Ob, char* lds) {
;     ...
;   SLOAD(0, 0); SLOAD(1, KVBLK); asm volatile("s_waitcnt vmcnt(0)" ::: "memory"); SWRITE(0, 0); SWRITE(1, 1); SLOAD(0, 2 * KVBLK); ABAR();
;   qkt(pA0, pA1, K_lds, qr, negm, r32, hi); partialSM<true>(pA0, pA1, mref, negm, alA);
;   SWRITE(2, 0); SLOAD(1, 3 * KVBLK); ABAR();
	v_mfma_f32_32x32x16_bf16 v[16:31], v[50:53], v[112:115], v[16:31]
	v_max_f32_e32 v48, v49, v48
	v_max3_f32 v48, v48, v34, v35
	v_max3_f32 v48, v48, v36, v37
	v_max3_f32 v48, v48, v38, v39
	v_max3_f32 v48, v48, v40, v41
	v_max3_f32 v48, v48, v42, v43
	v_max3_f32 v48, v48, v44, v45
	v_max3_f32 v48, v48, v46, v47
	s_nop 3
	v_max3_f32 v48, v48, v16, v17
	v_max3_f32 v48, v48, v18, v19
	v_max3_f32 v48, v48, v20, v21
	v_max3_f32 v48, v48, v22, v23
	v_max3_f32 v48, v48, v24, v25
	v_max3_f32 v48, v48, v26, v27
	v_max3_f32 v48, v48, v28, v29
	v_max3_f32 v48, v48, v30, v31
	v_mov_b32_e32 v49, v48
	s_nop 1
	v_permlane32_swap_b32_e32 v48, v49
	v_max_f32_e32 v49, v49, v49
	v_max_f32_e32 v48, v48, v48
	v_max_f32_e32 v48, v48, v49
	v_sub_f32_e32 v64, v16, v48
	v_add_u32_e32 v16, s83, v201
	v_sub_f32_e32 v49, v32, v48
	v_sub_f32_e32 v33, v33, v48
	v_sub_f32_e32 v34, v34, v48
	v_sub_f32_e32 v35, v35, v48
	v_sub_f32_e32 v36, v36, v48
	v_sub_f32_e32 v37, v37, v48
	v_sub_f32_e32 v38, v38, v48
	v_sub_f32_e32 v39, v39, v48
	v_sub_f32_e32 v40, v40, v48
	v_sub_f32_e32 v41, v41, v48
	v_sub_f32_e32 v42, v42, v48
	v_sub_f32_e32 v43, v43, v48
	v_sub_f32_e32 v44, v44, v48
	v_sub_f32_e32 v45, v45, v48
	v_sub_f32_e32 v46, v46, v48
	v_sub_f32_e32 v47, v47, v48
	s_waitcnt vmcnt(4)
	ds_write_b128 v16, v[140:143]
	v_add_u32_e32 v16, s83, v202
	v_exp_f32_e32 v194, v49
	v_exp_f32_e32 v216, v33
	v_exp_f32_e32 v192, v34
	v_exp_f32_e32 v195, v35
	v_exp_f32_e32 v190, v36
	v_exp_f32_e32 v193, v37
	v_exp_f32_e32 v189, v38
	v_exp_f32_e32 v191, v39
	v_exp_f32_e32 v186, v40
	v_exp_f32_e32 v188, v41
	v_exp_f32_e32 v185, v42
	v_exp_f32_e32 v187, v43
	v_exp_f32_e32 v181, v44
	v_exp_f32_e32 v183, v45
	v_exp_f32_e32 v180, v46
	v_exp_f32_e32 v182, v47
	s_waitcnt vmcnt(3)
	ds_write_b64 v16, v[172:173]
	v_add_f32_e32 v161, 0, v48
	s_waitcnt lgkmcnt(0)
	s_barrier
	v_sub_f32_e32 v79, v31, v48
	v_sub_f32_e32 v78, v30, v48
	v_sub_f32_e32 v77, v29, v48
	v_sub_f32_e32 v76, v28, v48
	v_sub_f32_e32 v75, v27, v48
	v_sub_f32_e32 v74, v26, v48
	v_sub_f32_e32 v73, v25, v48
	v_sub_f32_e32 v72, v24, v48
	v_sub_f32_e32 v71, v23, v48
	v_sub_f32_e32 v70, v22, v48
	v_sub_f32_e32 v69, v21, v48
	v_sub_f32_e32 v68, v20, v48
	v_sub_f32_e32 v67, v19, v48
	v_sub_f32_e32 v66, v18, v48
	v_sub_f32_e32 v65, v17, v48
	v_xor_b32_e32 v32, 0x80000000, v161
	v_mov_b64_e32 v[30:31], v[14:15]
	v_mov_b64_e32 v[28:29], v[12:13]
	v_mov_b64_e32 v[26:27], v[10:11]
	v_mov_b64_e32 v[24:25], v[8:9]
	v_mov_b64_e32 v[22:23], v[6:7]
	v_mov_b64_e32 v[20:21], v[4:5]
	v_mov_b64_e32 v[18:19], v[2:3]
	v_mov_b64_e32 v[16:17], v[0:1]
	v_mov_b32_e32 v33, v32
	v_mov_b32_e32 v34, v32
	v_mov_b32_e32 v35, v32
	v_mov_b32_e32 v36, v32
	v_mov_b32_e32 v37, v32
	v_mov_b32_e32 v38, v32
	v_mov_b32_e32 v39, v32
	v_mov_b32_e32 v40, v32
	v_mov_b32_e32 v41, v32
	v_mov_b32_e32 v42, v32
	v_mov_b32_e32 v43, v32
	v_mov_b32_e32 v44, v32
	v_mov_b32_e32 v45, v32
	v_mov_b32_e32 v46, v32
	v_mov_b32_e32 v47, v32
; #define LAS __attribute__((address_space(3)))
; __device__ __forceinline__ void qkt(f32x16& p0, f32x16& p1, const char* Ks, const bf16x8* qr, const f32x16& negm, int r32, int hi) {
;   p0 = negm; p1 = negm;
; #pragma unroll
;   for (int d0 = 0; d0 < 6; ++d0) { int cb = (d0 * 16 + hi * 8) * 2;
;     bf16x8 b0 = *reinterpret_cast<const bf16x8*>(Ks + KSWZ(r32, cb));
;     bf16x8 b1 = *reinterpret_cast<const bf16x8*>(Ks + KSWZ(32 + r32, cb));
;     p0 = __builtin_amdgcn_mfma_f32_32x32x16_bf16(b0, qr[d0], p0, 0, 0, 0);
;     p1 = __builtin_amdgcn_mfma_f32_32x32x16_bf16(b1, qr[d0], p1, 0, 0, 0); }
; }
; __device__ __forceinline__ int v_st(int k, int c) { const int kk = k; return ((kk >> 3) * 4 + (c >> 5)) * 512 + ((kk & 7) * 32 + (c & 31)) * 2; }
; __device__ __forceinline__ int v_rd_base(int lane) { return ((lane & 3) << 3) | (((lane >> 2) & 3) << 6) | (((lane >> 4) & 1) << 5) | (((lane >> 5) & 1) << 8); }
; __device__ __forceinline__ s16x4 vtr(lds_cptr p) { return __builtin_bit_cast(s16x4, __builtin_amdgcn_ds_read_tr16_b64_v4i16((LAS v4i16_t*)p)); }
; template <int D0> __device__ __forceinline__ void pv_one(f32x16& od, lds_cptr vp, bf16x8 pa0, bf16x8 pa1, bf16x8 pa2, bf16x8 pa3) {
;   const s16x4 l0 = vtr(vp + v_rd_off(D0, 0, 0)), h0 = vtr(vp + v_rd_off(D0, 0, 1)), l1 = vtr(vp + v_rd_off(D0, 1, 0)), h1 = vtr(vp + v_rd_off(D0, 1, 1));
;   const s16x4 l2 = vtr(vp + v_rd_off(D0, 2, 0)), h2 = vtr(vp + v_rd_off(D0, 2, 1)), l3 = vtr(vp + v_rd_off(D0, 3, 0)), h3 = vtr(vp + v_rd_off(D0, 3, 1));
;     ...
;   od = __builtin_amdgcn_mfma_f32_32x32x16_bf16(pa0, PK(l0, h0), od, 0, 0, 0);
;   od = __builtin_amdgcn_mfma_f32_32x32x16_bf16(pa1, PK(l1, h1), od, 0, 0, 0);
;   od = __builtin_amdgcn_mfma_f32_32x32x16_bf16(pa2, PK(l2, h2), od, 0, 0, 0);
; __device__ __forceinline__ void attn_unit(const bf16_t* __restrict__ Qb, const bf16_t* __restrict__ KNh, const bf16_t* __restrict__ KRb, const bf16_t* __restrict__ Vh, bf16_t* __restrict__ Ob, char* lds) {
;     ...
;   for (int j = 1; j + 1 < NT; j += 2) {
;     SBAR(); qkt(pB0, pB1, K_lds + (j & 3) * SHM_K, qr, negm, r32, hi);
;     finishSM(pA0, pA1, alA, l_reg, pa0, pa1, pa2, pa3); SBAR();
;     if (j + 2 < NT) { SWRITE((j + 2) & 3, 1); } if (j + 3 < NT) { SLOAD(0, (j + 3) * KVBLK); } SBAR();
;     pv_d0(o, vb0 + ((j - 1) & 3) * SHM_V, pa0, pa1, pa2, pa3); partialSM<false>(pB0, pB1, mref, negm, alB);
;     RESC(alB); ABAR();
.Lattn_f4:
	s_add_i32 s41, s89, 0xffff4000
	s_and_b32 s41, s41, 0xc000
	s_add_i32 s42, s85, s41
	ds_read_b128 v[48:51], v243 offset:16384
	ds_read_b128 v[52:55], v243 offset:24576
	s_waitcnt lgkmcnt(1)
	v_mfma_f32_32x32x16_bf16 v[96:111], v[48:51], v[132:135], v[32:47]
	ds_read_b128 v[48:51], v244 offset:16384
	ds_read_b128 v[56:59], v244 offset:24576
	v_exp_f32_e32 v64, v64
	v_exp_f32_e32 v65, v65
	v_exp_f32_e32 v66, v66
	v_exp_f32_e32 v67, v67
	v_exp_f32_e32 v68, v68
	s_waitcnt lgkmcnt(2)
	v_mfma_f32_32x32x16_bf16 v[80:95], v[52:55], v[132:135], v[32:47]
	ds_read_b128 v[52:55], v245 offset:16384
	ds_read_b128 v[60:63], v245 offset:24576
	ds_read_b128 v[220:223], v246 offset:16384
	ds_read_b128 v[224:227], v246 offset:24576
	ds_read_b128 v[228:231], v247 offset:16384
	ds_read_b128 v[232:235], v247 offset:24576
	v_exp_f32_e32 v69, v69
	v_exp_f32_e32 v70, v70
	v_exp_f32_e32 v71, v71
	v_exp_f32_e32 v72, v72
	v_exp_f32_e32 v73, v73
	s_waitcnt lgkmcnt(7)
	v_mfma_f32_32x32x16_bf16 v[96:111], v[48:51], v[128:131], v[96:111]
	ds_read_b128 v[48:51], v248 offset:16384
	ds_read_b128 v[236:239], v248 offset:24576
	v_exp_f32_e32 v74, v74
	v_exp_f32_e32 v75, v75
	v_exp_f32_e32 v76, v76
	v_exp_f32_e32 v77, v77
	v_exp_f32_e32 v78, v78
	v_exp_f32_e32 v79, v79
	s_waitcnt lgkmcnt(8)
	v_mfma_f32_32x32x16_bf16 v[80:95], v[56:59], v[128:131], v[80:95]
	s_waitcnt lgkmcnt(7)
	v_mfma_f32_32x32x16_bf16 v[96:111], v[52:55], v[124:127], v[96:111]
	v_fma_f32 v52, v163, v152, v194
	v_add_f32_e32 v52, v216, v52
	v_add_f32_e32 v52, v192, v52
	v_add_f32_e32 v52, v195, v52
	v_add_f32_e32 v52, v190, v52
	v_add_f32_e32 v52, v193, v52
	v_add_f32_e32 v52, v189, v52
	s_waitcnt lgkmcnt(6)
	v_mfma_f32_32x32x16_bf16 v[80:95], v[60:63], v[124:127], v[80:95]
	v_add_f32_e32 v52, v191, v52
	v_add_f32_e32 v52, v186, v52
	v_add_f32_e32 v52, v188, v52
	v_add_f32_e32 v52, v185, v52
	v_add_f32_e32 v52, v187, v52
	v_add_f32_e32 v52, v181, v52
	v_add_f32_e32 v52, v183, v52
	s_waitcnt lgkmcnt(5)
	v_mfma_f32_32x32x16_bf16 v[96:111], v[220:223], v[120:123], v[96:111]
	v_add_f32_e32 v52, v180, v52
	v_add_f32_e32 v52, v182, v52
	v_add_f32_e32 v52, v64, v52
	v_add_f32_e32 v52, v65, v52
	v_add_f32_e32 v52, v66, v52
	v_add_f32_e32 v52, v67, v52
	v_add_f32_e32 v52, v68, v52
	s_waitcnt lgkmcnt(4)
	v_mfma_f32_32x32x16_bf16 v[80:95], v[224:227], v[120:123], v[80:95]
	v_add_f32_e32 v52, v69, v52
	v_add_f32_e32 v52, v70, v52
	v_add_f32_e32 v52, v71, v52
	v_add_f32_e32 v52, v72, v52
	v_add_f32_e32 v52, v73, v52
	v_add_f32_e32 v52, v74, v52
	v_add_f32_e32 v52, v75, v52
	s_waitcnt lgkmcnt(3)
	v_mfma_f32_32x32x16_bf16 v[96:111], v[228:231], v[116:119], v[96:111]
	v_add_f32_e32 v52, v76, v52
	v_add_f32_e32 v52, v77, v52
	v_add_f32_e32 v52, v78, v52
	v_add_f32_e32 v165, v79, v52
	s_waitcnt lgkmcnt(2)
	v_mfma_f32_32x32x16_bf16 v[80:95], v[232:235], v[116:119], v[80:95]
	v_cvt_pk_bf16_f32 v60, v194, v216
	v_cvt_pk_bf16_f32 v61, v192, v195
	v_cvt_pk_bf16_f32 v62, v190, v193
	v_cvt_pk_bf16_f32 v63, v189, v191
	v_cvt_pk_bf16_f32 v56, v186, v188
	v_cvt_pk_bf16_f32 v57, v185, v187
	v_cvt_pk_bf16_f32 v58, v181, v183
	s_waitcnt lgkmcnt(1)
	v_mfma_f32_32x32x16_bf16 v[96:111], v[48:51], v[112:115], v[96:111]
	v_cvt_pk_bf16_f32 v59, v180, v182
	v_cvt_pk_bf16_f32 v52, v64, v65
	v_cvt_pk_bf16_f32 v53, v66, v67
	v_cvt_pk_bf16_f32 v54, v68, v69
	v_cvt_pk_bf16_f32 v55, v70, v71
	v_cvt_pk_bf16_f32 v48, v72, v73
	v_cvt_pk_bf16_f32 v49, v74, v75
	s_waitcnt lgkmcnt(0)
	v_mfma_f32_32x32x16_bf16 v[80:95], v[236:239], v[112:115], v[80:95]
	v_cvt_pk_bf16_f32 v50, v76, v77
	v_cvt_pk_bf16_f32 v51, v78, v79
	s_add_i32 s42, s89, 0xffffc000
	s_and_b32 s42, s42, 0xc000
	s_add_i32 s43, s85, s42
	s_cmp_lt_u32 s90, 29
	s_cselect_b64 s[44:45], -1, 0
	s_cmp_gt_u32 s90, 28
	s_cselect_b64 s[42:43], -1, 0
	s_and_b64 vcc, exec, s[42:43]
	s_waitcnt vmcnt(2)
	ds_write_b128 v204, v[144:147] offset:49152
	s_waitcnt vmcnt(1)
	ds_write_b128 v249, v[148:151] offset:49152
	s_waitcnt vmcnt(0)
	ds_write_b64 v250, v[174:175] offset:49152
	s_cbranch_vccnz .Lf1_741
	global_load_dwordx4 v[136:139], v240, s[98:99]
	global_load_dwordx4 v[140:143], v241, s[98:99]
	global_load_dwordx2 v[172:173], v242, s[100:101]
	s_add_u32 s98, s98, 0x10000
	s_addc_u32 s99, s99, 0
	s_add_u32 s100, s100, 0x1000
	s_addc_u32 s101, s101, 0
.Lf1_741:
	s_and_b32 s48, s89, 0xc000
	ds_read_b64_tr_b16 v[64:65], v203
	ds_read_b64_tr_b16 v[66:67], v203 offset:2048
	ds_read_b64_tr_b16 v[70:71], v203 offset:2560
	ds_read_b64_tr_b16 v[68:69], v203 offset:512
	s_waitcnt lgkmcnt(2)
	v_mfma_f32_32x32x16_bf16 v[0:15], v[60:63], v[64:67], v[0:15]
	ds_read_b64_tr_b16 v[64:65], v203 offset:4096
	ds_read_b64_tr_b16 v[66:67], v203 offset:6144
	ds_read_b64_tr_b16 v[74:75], v203 offset:6656
	ds_read_b64_tr_b16 v[72:73], v203 offset:4608
	s_waitcnt lgkmcnt(2)
	v_mfma_f32_32x32x16_bf16 v[0:15], v[56:59], v[64:67], v[0:15]
	ds_read_b64_tr_b16 v[64:65], v203 offset:8192
	ds_read_b64_tr_b16 v[66:67], v203 offset:10240
	ds_read_b64_tr_b16 v[78:79], v203 offset:10752
	ds_read_b64_tr_b16 v[76:77], v203 offset:8704
	v_mfma_f32_32x32x16_bf16 v[16:31], v[60:63], v[68:71], v[16:31]
	s_waitcnt lgkmcnt(2)
	v_mfma_f32_32x32x16_bf16 v[0:15], v[52:55], v[64:67], v[0:15]
	ds_read_b64_tr_b16 v[64:65], v203 offset:12288
	ds_read_b64_tr_b16 v[66:67], v203 offset:14336
	ds_read_b64_tr_b16 v[186:187], v203 offset:14848
	ds_read_b64_tr_b16 v[184:185], v203 offset:12800
	v_mfma_f32_32x32x16_bf16 v[16:31], v[56:59], v[72:75], v[16:31]
	s_waitcnt lgkmcnt(2)
	v_mfma_f32_32x32x16_bf16 v[0:15], v[48:51], v[64:67], v[0:15]
	v_max_f32_e32 v64, v97, v97
	v_max_f32_e32 v65, v96, v96
	v_max_f32_e32 v64, v65, v64
	v_max3_f32 v64, v64, v98, v99
	v_max3_f32 v60, v64, v100, v101
	v_max3_f32 v60, v60, v102, v103
	v_max3_f32 v60, v60, v104, v105
	v_max3_f32 v60, v60, v106, v107
	v_max3_f32 v60, v60, v108, v109
	v_mfma_f32_32x32x16_bf16 v[16:31], v[52:55], v[76:79], v[16:31]
	v_max3_f32 v60, v60, v110, v111
	v_max3_f32 v60, v60, v80, v81
	v_max3_f32 v56, v60, v82, v83
	v_max3_f32 v56, v56, v84, v85
	v_max3_f32 v56, v56, v86, v87
	v_max3_f32 v56, v56, v88, v89
	v_max3_f32 v56, v56, v90, v91
	v_max3_f32 v56, v56, v92, v93
	s_waitcnt lgkmcnt(0)
	v_mfma_f32_32x32x16_bf16 v[16:31], v[48:51], v[184:187], v[16:31]
	v_max3_f32 v56, v56, v94, v95
	v_mov_b32_e32 v52, v56
	s_nop 1
	v_permlane32_swap_b32_e32 v56, v52
	v_max_f32_e32 v52, v52, v52
	v_max_f32_e32 v53, v56, v56
	v_max_f32_e32 v52, v53, v52
	v_cmp_ge_f32_e32 vcc, s86, v52
	s_cmp_eq_u64 vcc, exec
	s_cbranch_scc0 .Lf1_757
	v_mov_b32_e32 v169, 1.0
	v_cmp_gt_f32_e32 vcc, 1.0, v169
	s_cbranch_vccz .Lf1_746

; #define SBAR() __builtin_amdgcn_sched_barrier(0)
; #define PK4(P, BASE, OUT) do { u32x4 w = {cvt_pk_bf16(P[BASE + 0], P[BASE + 1]), cvt_pk_bf16(P[BASE + 2], P[BASE + 3]), cvt_pk_bf16(P[BASE + 4], P[BASE + 5]), cvt_pk_bf16(P[BASE + 6], P[BASE + 7])}; \
;     OUT = *reinterpret_cast<bf16x8*>(&w); } while (0)
; #define SLOAD(i, k0) do { const bf16_t* vt_ = Vh + (size_t)(k0) * 512; const bf16_t* kt_ = KNh + (size_t)(k0) * 512; const bf16_t* rt_ = KRb + (size_t)(k0) * 32; \
;     sr_[i].vs = *reinterpret_cast<const bf16x8*>(vt_ + lo_kv); sr_[i].ks = *reinterpret_cast<const bf16x8*>(kt_ + lo_kv); sr_[i].kr = *reinterpret_cast<const s16x4*>(rt_ + lo_kr); } while (0)
; __device__ __forceinline__ void finishSM(f32x16& p0, f32x16& p1, float alpha, float& l_reg, bf16x8& pa0, bf16x8& pa1, bf16x8& pa2, bf16x8& pa3) {
; #pragma unroll
;   for (int r = 0; r < 16; ++r) p1[r] = __builtin_amdgcn_exp2f(p1[r]);
;   float ps = 0;
; #pragma unroll
;   for (int r = 0; r < 16; ++r) ps += p0[r];
; #pragma unroll
;   for (int r = 0; r < 16; ++r) ps += p1[r];
;   { auto rr = __builtin_amdgcn_permlane32_swap(__float_as_uint(ps), __float_as_uint(ps), false, false);
;     ps = __uint_as_float(rr[0]) + __uint_as_float(rr[1]); }
;   l_reg = l_reg * alpha + ps;
;     ...
;   PK4(p0, 0, pa0); PK4(p0, 8, pa1); PK4(p1, 0, pa2); PK4(p1, 8, pa3);
;     ...
; }
; __device__ __forceinline__ void qkt(f32x16& p0, f32x16& p1, const char* Ks, const bf16x8* qr, const f32x16& negm, int r32, int hi) {
;   p0 = negm; p1 = negm;
; #pragma unroll
;   for (int d0 = 0; d0 < 6; ++d0) { int cb = (d0 * 16 + hi * 8) * 2;
;     bf16x8 b0 = *reinterpret_cast<const bf16x8*>(Ks + KSWZ(r32, cb));
;     bf16x8 b1 = *reinterpret_cast<const bf16x8*>(Ks + KSWZ(32 + r32, cb));
;     p0 = __builtin_amdgcn_mfma_f32_32x32x16_bf16(b0, qr[d0], p0, 0, 0, 0);
;     p1 = __builtin_amdgcn_mfma_f32_32x32x16_bf16(b1, qr[d0], p1, 0, 0, 0); }
; }
; __device__ __forceinline__ void attn_unit(const bf16_t* __restrict__ Qb, const bf16_t* __restrict__ KNh, const bf16_t* __restrict__ KRb, const bf16_t* __restrict__ Vh, bf16_t* __restrict__ Ob, char* lds) {
;     ...
;     SBAR(); qkt(pA0, pA1, K_lds + ((j + 1) & 3) * SHM_K, qr, negm, r32, hi);
;     finishSM(pB0, pB1, alB, l_reg, pa0, pa1, pa2, pa3); SBAR();
;     if (j + 3 < NT) { SWRITE((j + 3) & 3, 0); } if (j + 4 < NT) { SLOAD(1, (j + 4) * KVBLK); } SBAR();
.Lf1_746:
	s_waitcnt lgkmcnt(0)
	s_barrier
	v_exp_f32_e32 v192, v96
	v_exp_f32_e32 v193, v97
	v_exp_f32_e32 v194, v98
	v_exp_f32_e32 v195, v99
	v_exp_f32_e32 v216, v100
	v_exp_f32_e32 v217, v101
	v_exp_f32_e32 v219, v102
	v_exp_f32_e32 v220, v103
	v_exp_f32_e32 v221, v104
	v_exp_f32_e32 v222, v105
	v_exp_f32_e32 v223, v106
	v_exp_f32_e32 v224, v107
	v_exp_f32_e32 v225, v108
	v_exp_f32_e32 v226, v109
	v_exp_f32_e32 v227, v110
	v_exp_f32_e32 v228, v111
	s_add_i32 s46, s89, 0xffff8000
	s_and_b32 s46, s46, 0xc000
	s_add_i32 s46, s46, 0
	s_add_i32 s46, s46, 0x10000
	ds_read_b128 v[64:67], v243 offset:32768
	ds_read_b128 v[184:187], v243 offset:40960
	v_exp_f32_e32 v80, v80
	v_exp_f32_e32 v81, v81
	s_waitcnt lgkmcnt(1)
	v_mfma_f32_32x32x16_bf16 v[96:111], v[64:67], v[132:135], v[32:47]
	v_exp_f32_e32 v82, v82
	v_exp_f32_e32 v83, v83
	v_exp_f32_e32 v87, v87
	v_exp_f32_e32 v229, v92
	v_exp_f32_e32 v230, v93
	v_exp_f32_e32 v231, v94
	v_exp_f32_e32 v232, v95
	s_waitcnt lgkmcnt(0)
	v_mfma_f32_32x32x16_bf16 v[64:79], v[184:187], v[132:135], v[32:47]
	ds_read_b128 v[184:187], v244 offset:32768
	ds_read_b128 v[188:191], v244 offset:40960
	s_waitcnt lgkmcnt(1)
	v_mfma_f32_32x32x16_bf16 v[96:111], v[184:187], v[128:131], v[96:111]
	s_waitcnt lgkmcnt(0)
	v_mfma_f32_32x32x16_bf16 v[64:79], v[188:191], v[128:131], v[64:79]
	ds_read_b128 v[184:187], v245 offset:32768
	ds_read_b128 v[188:191], v245 offset:40960
	s_waitcnt lgkmcnt(1)
	v_mfma_f32_32x32x16_bf16 v[96:111], v[184:187], v[124:127], v[96:111]
	s_waitcnt lgkmcnt(0)
	v_mfma_f32_32x32x16_bf16 v[64:79], v[188:191], v[124:127], v[64:79]
	ds_read_b128 v[184:187], v246 offset:32768
	ds_read_b128 v[188:191], v246 offset:40960
	s_waitcnt lgkmcnt(1)
	v_mfma_f32_32x32x16_bf16 v[96:111], v[184:187], v[120:123], v[96:111]
	s_waitcnt lgkmcnt(0)
	v_mfma_f32_32x32x16_bf16 v[64:79], v[188:191], v[120:123], v[64:79]
	ds_read_b128 v[184:187], v247 offset:32768
	ds_read_b128 v[188:191], v247 offset:40960
	s_waitcnt lgkmcnt(1)
	v_mfma_f32_32x32x16_bf16 v[96:111], v[184:187], v[116:119], v[96:111]
	s_waitcnt lgkmcnt(0)
	v_mfma_f32_32x32x16_bf16 v[64:79], v[188:191], v[116:119], v[64:79]
	ds_read_b128 v[184:187], v248 offset:32768
	ds_read_b128 v[188:191], v248 offset:40960
	v_cvt_pk_bf16_f32 v92, v192, v193
	v_cvt_pk_bf16_f32 v93, v194, v195
	v_cvt_pk_bf16_f32 v94, v216, v217
	v_cvt_pk_bf16_f32 v95, v219, v220
	s_waitcnt lgkmcnt(1)
	v_mfma_f32_32x32x16_bf16 v[96:111], v[184:187], v[112:115], v[96:111]
	v_exp_f32_e32 v185, v84
	v_fma_f32 v84, v165, v169, v192
	v_add_f32_e32 v84, v193, v84
	v_add_f32_e32 v84, v194, v84
	v_add_f32_e32 v84, v195, v84
	v_add_f32_e32 v84, v216, v84
	v_add_f32_e32 v84, v217, v84
	v_add_f32_e32 v84, v219, v84
	v_add_f32_e32 v84, v220, v84
	v_add_f32_e32 v84, v221, v84
	v_add_f32_e32 v84, v222, v84
	v_add_f32_e32 v84, v223, v84
	v_add_f32_e32 v84, v224, v84
	v_add_f32_e32 v84, v225, v84
	v_add_f32_e32 v84, v226, v84
	v_add_f32_e32 v84, v227, v84
	v_add_f32_e32 v84, v228, v84
	v_add_f32_e32 v84, v80, v84
	v_exp_f32_e32 v186, v85
	v_add_f32_e32 v84, v81, v84
	v_exp_f32_e32 v187, v86
	v_add_f32_e32 v84, v82, v84
	v_add_f32_e32 v84, v83, v84
	s_waitcnt lgkmcnt(0)
	v_mfma_f32_32x32x16_bf16 v[64:79], v[188:191], v[112:115], v[64:79]
	v_exp_f32_e32 v188, v88
	v_add_f32_e32 v84, v185, v84
	v_exp_f32_e32 v189, v89
	v_add_f32_e32 v84, v186, v84
	v_exp_f32_e32 v190, v90
	v_add_f32_e32 v84, v187, v84
	v_exp_f32_e32 v191, v91
	v_add_f32_e32 v84, v87, v84
	v_add_f32_e32 v84, v188, v84
	v_add_f32_e32 v84, v189, v84
	v_add_f32_e32 v84, v190, v84
	v_add_f32_e32 v84, v191, v84
	v_add_f32_e32 v84, v229, v84
	v_add_f32_e32 v84, v230, v84
	v_add_f32_e32 v84, v231, v84
	v_add_f32_e32 v152, v232, v84
	v_cvt_pk_bf16_f32 v88, v221, v222
	v_cvt_pk_bf16_f32 v89, v223, v224
	v_cvt_pk_bf16_f32 v90, v225, v226
	v_cvt_pk_bf16_f32 v91, v227, v228
	v_cvt_pk_bf16_f32 v84, v80, v81
	v_cvt_pk_bf16_f32 v85, v82, v83
	v_cvt_pk_bf16_f32 v86, v185, v186
	v_cvt_pk_bf16_f32 v87, v187, v87
	v_cvt_pk_bf16_f32 v80, v188, v189
	v_cvt_pk_bf16_f32 v81, v190, v191
	v_cvt_pk_bf16_f32 v82, v229, v230
	v_cvt_pk_bf16_f32 v83, v231, v232
	s_andn2_b64 vcc, exec, s[44:45]
	s_cbranch_vccnz .Lf1_748
	s_add_i32 s44, s48, 0
	s_add_i32 s44, s44, 0x10000
	s_waitcnt vmcnt(2)
	ds_write_b128 v204, v[136:139]
	s_waitcnt vmcnt(1)
	ds_write_b128 v249, v[140:143]
	s_waitcnt vmcnt(0)
	ds_write_b64 v250, v[172:173]

; __device__ __forceinline__ s16x4 vtr(lds_cptr p) { return __builtin_bit_cast(s16x4, __builtin_amdgcn_ds_read_tr16_b64_v4i16((LAS v4i16_t*)p)); }
; template <bool FIRST> __device__ __forceinline__ void partialSM(f32x16& p0, f32x16& p1, float& mref, f32x16& negm, float& alpha) {
;   constexpr float THRL = THR * 1.4426950408889634f;
;   float pmax = p0[0];
; #pragma unroll
;   for (int r = 1; r < 16; ++r) pmax = fmaxf(pmax, p0[r]);
; #pragma unroll
;   for (int r = 0; r < 16; ++r) pmax = fmaxf(pmax, p1[r]);
;   { auto rr = __builtin_amdgcn_permlane32_swap(__float_as_uint(pmax), __float_as_uint(pmax), false, false);
;     pmax = fmaxf(__uint_as_float(rr[0]), __uint_as_float(rr[1])); }
;   if (!FIRST && __builtin_expect(__all(pmax <= THRL), 1)) { alpha = 1.f; }
; template <int D0> __device__ __forceinline__ void pv_one(f32x16& od, lds_cptr vp, bf16x8 pa0, bf16x8 pa1, bf16x8 pa2, bf16x8 pa3) {
;   const s16x4 l0 = vtr(vp + v_rd_off(D0, 0, 0)), h0 = vtr(vp + v_rd_off(D0, 0, 1)), l1 = vtr(vp + v_rd_off(D0, 1, 0)), h1 = vtr(vp + v_rd_off(D0, 1, 1));
;   const s16x4 l2 = vtr(vp + v_rd_off(D0, 2, 0)), h2 = vtr(vp + v_rd_off(D0, 2, 1)), l3 = vtr(vp + v_rd_off(D0, 3, 0)), h3 = vtr(vp + v_rd_off(D0, 3, 1));
;     ...
;   od = __builtin_amdgcn_mfma_f32_32x32x16_bf16(pa0, PK(l0, h0), od, 0, 0, 0);
;   od = __builtin_amdgcn_mfma_f32_32x32x16_bf16(pa1, PK(l1, h1), od, 0, 0, 0);
;   od = __builtin_amdgcn_mfma_f32_32x32x16_bf16(pa2, PK(l2, h2), od, 0, 0, 0);
;   od = __builtin_amdgcn_mfma_f32_32x32x16_bf16(pa3, PK(l3, h3), od, 0, 0, 0);
;     ...
; }
; __device__ __forceinline__ void pv_d0(f32x16* o, lds_cptr vp, bf16x8 pa0, bf16x8 pa1, bf16x8 pa2, bf16x8 pa3) {
;   pv_one<0>(o[0], vp, pa0, pa1, pa2, pa3); pv_one<1>(o[1], vp, pa0, pa1, pa2, pa3);
; }
.Lf1_750:
	ds_read_b64_tr_b16 v[180:181], v203 offset:16384
	ds_read_b64_tr_b16 v[182:183], v203 offset:18432
	ds_read_b64_tr_b16 v[188:189], v203 offset:18944
	ds_read_b64_tr_b16 v[186:187], v203 offset:16896
	s_waitcnt lgkmcnt(2)
	v_mfma_f32_32x32x16_bf16 v[0:15], v[92:95], v[180:183], v[0:15]
	ds_read_b64_tr_b16 v[180:181], v203 offset:20480
	ds_read_b64_tr_b16 v[182:183], v203 offset:22528
	ds_read_b64_tr_b16 v[192:193], v203 offset:23040
	ds_read_b64_tr_b16 v[190:191], v203 offset:20992
	s_waitcnt lgkmcnt(2)
	v_mfma_f32_32x32x16_bf16 v[0:15], v[88:91], v[180:183], v[0:15]
	ds_read_b64_tr_b16 v[180:181], v203 offset:24576
	ds_read_b64_tr_b16 v[182:183], v203 offset:26624
	ds_read_b64_tr_b16 v[222:223], v203 offset:27136
	ds_read_b64_tr_b16 v[220:221], v203 offset:25088
	v_mfma_f32_32x32x16_bf16 v[16:31], v[92:95], v[186:189], v[16:31]
	s_waitcnt lgkmcnt(2)
	v_mfma_f32_32x32x16_bf16 v[0:15], v[84:87], v[180:183], v[0:15]
	ds_read_b64_tr_b16 v[180:181], v203 offset:28672
	ds_read_b64_tr_b16 v[182:183], v203 offset:30720
	ds_read_b64_tr_b16 v[226:227], v203 offset:31232
	ds_read_b64_tr_b16 v[224:225], v203 offset:29184
	v_mfma_f32_32x32x16_bf16 v[16:31], v[88:91], v[190:193], v[16:31]
	s_waitcnt lgkmcnt(2)
	v_mfma_f32_32x32x16_bf16 v[0:15], v[80:83], v[180:183], v[0:15]
	v_max_f32_e32 v180, v97, v97
	v_max_f32_e32 v181, v96, v96
	v_max_f32_e32 v180, v181, v180
	v_max3_f32 v180, v180, v98, v99
	v_max3_f32 v180, v180, v100, v101
	v_max3_f32 v92, v180, v102, v103
	v_max3_f32 v92, v92, v104, v105
	v_max3_f32 v92, v92, v106, v107
	v_max3_f32 v92, v92, v108, v109
	v_mfma_f32_32x32x16_bf16 v[16:31], v[84:87], v[220:223], v[16:31]
	v_max3_f32 v92, v92, v110, v111
	v_max3_f32 v92, v92, v64, v65
	v_max3_f32 v92, v92, v66, v67
	v_max3_f32 v88, v92, v68, v69
	v_max3_f32 v88, v88, v70, v71
	v_max3_f32 v88, v88, v72, v73
	v_max3_f32 v88, v88, v74, v75
	v_max3_f32 v88, v88, v76, v77
	s_waitcnt lgkmcnt(0)
	v_mfma_f32_32x32x16_bf16 v[16:31], v[80:83], v[224:227], v[16:31]
	v_max3_f32 v88, v88, v78, v79
	v_mov_b32_e32 v89, v88
	s_nop 1
	v_permlane32_swap_b32_e32 v88, v89
	v_max_f32_e32 v84, v89, v89
	v_max_f32_e32 v85, v88, v88
	v_max_f32_e32 v85, v85, v84
	v_cmp_ge_f32_e32 vcc, s86, v85
	s_cmp_eq_u64 vcc, exec
	v_mov_b32_e32 v84, 1.0
	s_cbranch_scc0 .Lf1_758
	v_cmp_gt_f32_e32 vcc, 1.0, v84
	s_cbranch_vccz .Lf1_755

; #define SBAR() __builtin_amdgcn_sched_barrier(0)
; #define ABAR() asm volatile("s_waitcnt lgkmcnt(0)\n\ts_barrier" ::: "memory")
; #define SLOAD(i, k0) do { const bf16_t* vt_ = Vh + (size_t)(k0) * 512; const bf16_t* kt_ = KNh + (size_t)(k0) * 512; const bf16_t* rt_ = KRb + (size_t)(k0) * 32; \
;     sr_[i].vs = *reinterpret_cast<const bf16x8*>(vt_ + lo_kv); sr_[i].ks = *reinterpret_cast<const bf16x8*>(kt_ + lo_kv); sr_[i].kr = *reinterpret_cast<const s16x4*>(rt_ + lo_kr); } while (0)
; #define SWRITE(slot, i) do { *(bf16x8*)(V_lds + (slot) * SHM_V + vst) = sr_[i].vs; *(bf16x8*)(K_lds + (slot) * SHM_K + kst) = sr_[i].ks; *(s16x4*)(K_lds + (slot) * SHM_K + krst) = sr_[i].kr; } while (0)
; #define RESC(a) do { if (__any((a) < 1.f)) { if (hi == 0) al_l[r32] = (a); asm volatile("s_waitcnt lgkmcnt(0)" ::: "memory"); \
;     _Pragma("unroll") for (int d = 0; d < 2; ++d) _Pragma("unroll") for (int r = 0; r < 16; ++r) o[d][r] *= al_l[crow(r, hi)]; } } while (0)
; __device__ __forceinline__ void qkt(f32x16& p0, f32x16& p1, const char* Ks, const bf16x8* qr, const f32x16& negm, int r32, int hi) {
;   p0 = negm; p1 = negm;
; #pragma unroll
;   for (int d0 = 0; d0 < 6; ++d0) { int cb = (d0 * 16 + hi * 8) * 2;
;     bf16x8 b0 = *reinterpret_cast<const bf16x8*>(Ks + KSWZ(r32, cb));
;     bf16x8 b1 = *reinterpret_cast<const bf16x8*>(Ks + KSWZ(32 + r32, cb));
;     p0 = __builtin_amdgcn_mfma_f32_32x32x16_bf16(b0, qr[d0], p0, 0, 0, 0);
;     p1 = __builtin_amdgcn_mfma_f32_32x32x16_bf16(b1, qr[d0], p1, 0, 0, 0); }
; }
; __device__ __forceinline__ void attn_unit(const bf16_t* __restrict__ Qb, const bf16_t* __restrict__ KNh, const bf16_t* __restrict__ KRb, const bf16_t* __restrict__ Vh, bf16_t* __restrict__ Ob, char* lds) {
;     ...
;   for (int j = 1; j + 1 < NT; j += 2) {
;     SBAR(); qkt(pB0, pB1, K_lds + (j & 3) * SHM_K, qr, negm, r32, hi);
;     finishSM(pA0, pA1, alA, l_reg, pa0, pa1, pa2, pa3); SBAR();
;     if (j + 2 < NT) { SWRITE((j + 2) & 3, 1); } if (j + 3 < NT) { SLOAD(0, (j + 3) * KVBLK); } SBAR();
;     pv_d0(o, vb0 + ((j - 1) & 3) * SHM_V, pa0, pa1, pa2, pa3); partialSM<false>(pB0, pB1, mref, negm, alB);
;     RESC(alB); ABAR();
.Lf1_755:
	v_exp_f32_e32 v194, v96
	v_exp_f32_e32 v216, v97
	v_exp_f32_e32 v192, v98
	v_exp_f32_e32 v195, v99
	v_exp_f32_e32 v190, v100
	v_exp_f32_e32 v193, v101
	v_exp_f32_e32 v189, v102
	v_exp_f32_e32 v191, v103
	v_exp_f32_e32 v186, v104
	v_exp_f32_e32 v188, v105
	v_exp_f32_e32 v185, v106
	v_exp_f32_e32 v187, v107
	v_exp_f32_e32 v181, v108
	v_exp_f32_e32 v183, v109
	v_exp_f32_e32 v180, v110
	v_exp_f32_e32 v182, v111
	s_waitcnt lgkmcnt(0)
	s_barrier
	s_add_i32 s90, s90, 2
	s_add_i32 s89, s89, 0x8000
	v_mov_b32_e32 v163, v84
	s_add_i32 s41, s89, 0xffff4000
	s_and_b32 s41, s41, 0xc000
	s_add_i32 s42, s85, s41
	ds_read_b128 v[48:51], v243 offset:49152
	ds_read_b128 v[52:55], v243 offset:57344
	s_waitcnt lgkmcnt(1)
	v_mfma_f32_32x32x16_bf16 v[96:111], v[48:51], v[132:135], v[32:47]
	ds_read_b128 v[48:51], v244 offset:49152
	ds_read_b128 v[56:59], v244 offset:57344
	v_exp_f32_e32 v64, v64
	v_exp_f32_e32 v65, v65
	v_exp_f32_e32 v66, v66
	v_exp_f32_e32 v67, v67
	v_exp_f32_e32 v68, v68
	s_waitcnt lgkmcnt(2)
	v_mfma_f32_32x32x16_bf16 v[80:95], v[52:55], v[132:135], v[32:47]
	ds_read_b128 v[52:55], v245 offset:49152
	ds_read_b128 v[60:63], v245 offset:57344
	ds_read_b128 v[220:223], v246 offset:49152
	ds_read_b128 v[224:227], v246 offset:57344
	ds_read_b128 v[228:231], v247 offset:49152
	ds_read_b128 v[232:235], v247 offset:57344
	v_exp_f32_e32 v69, v69
	v_exp_f32_e32 v70, v70
	v_exp_f32_e32 v71, v71
	v_exp_f32_e32 v72, v72
	v_exp_f32_e32 v73, v73
	s_waitcnt lgkmcnt(7)
	v_mfma_f32_32x32x16_bf16 v[96:111], v[48:51], v[128:131], v[96:111]
	ds_read_b128 v[48:51], v248 offset:49152
	ds_read_b128 v[236:239], v248 offset:57344
	v_exp_f32_e32 v74, v74
	v_exp_f32_e32 v75, v75
	v_exp_f32_e32 v76, v76
	v_exp_f32_e32 v77, v77
	v_exp_f32_e32 v78, v78
	v_exp_f32_e32 v79, v79
	s_waitcnt lgkmcnt(8)
	v_mfma_f32_32x32x16_bf16 v[80:95], v[56:59], v[128:131], v[80:95]
	s_waitcnt lgkmcnt(7)
	v_mfma_f32_32x32x16_bf16 v[96:111], v[52:55], v[124:127], v[96:111]
	v_fma_f32 v52, v163, v152, v194
	v_add_f32_e32 v52, v216, v52
	v_add_f32_e32 v52, v192, v52
	v_add_f32_e32 v52, v195, v52
	v_add_f32_e32 v52, v190, v52
	v_add_f32_e32 v52, v193, v52
	v_add_f32_e32 v52, v189, v52
	s_waitcnt lgkmcnt(6)
	v_mfma_f32_32x32x16_bf16 v[80:95], v[60:63], v[124:127], v[80:95]
	v_add_f32_e32 v52, v191, v52
	v_add_f32_e32 v52, v186, v52
	v_add_f32_e32 v52, v188, v52
	v_add_f32_e32 v52, v185, v52
	v_add_f32_e32 v52, v187, v52
	v_add_f32_e32 v52, v181, v52
	v_add_f32_e32 v52, v183, v52
	s_waitcnt lgkmcnt(5)
	v_mfma_f32_32x32x16_bf16 v[96:111], v[220:223], v[120:123], v[96:111]
	v_add_f32_e32 v52, v180, v52
	v_add_f32_e32 v52, v182, v52
	v_add_f32_e32 v52, v64, v52
	v_add_f32_e32 v52, v65, v52
	v_add_f32_e32 v52, v66, v52
	v_add_f32_e32 v52, v67, v52
	v_add_f32_e32 v52, v68, v52
	s_waitcnt lgkmcnt(4)
	v_mfma_f32_32x32x16_bf16 v[80:95], v[224:227], v[120:123], v[80:95]
	v_add_f32_e32 v52, v69, v52
	v_add_f32_e32 v52, v70, v52
	v_add_f32_e32 v52, v71, v52
	v_add_f32_e32 v52, v72, v52
	v_add_f32_e32 v52, v73, v52
	v_add_f32_e32 v52, v74, v52
	v_add_f32_e32 v52, v75, v52
	s_waitcnt lgkmcnt(3)
	v_mfma_f32_32x32x16_bf16 v[96:111], v[228:231], v[116:119], v[96:111]
	v_add_f32_e32 v52, v76, v52
	v_add_f32_e32 v52, v77, v52
	v_add_f32_e32 v52, v78, v52
	v_add_f32_e32 v165, v79, v52
	s_waitcnt lgkmcnt(2)
	v_mfma_f32_32x32x16_bf16 v[80:95], v[232:235], v[116:119], v[80:95]
	v_cvt_pk_bf16_f32 v60, v194, v216
	v_cvt_pk_bf16_f32 v61, v192, v195
	v_cvt_pk_bf16_f32 v62, v190, v193
	v_cvt_pk_bf16_f32 v63, v189, v191
	v_cvt_pk_bf16_f32 v56, v186, v188
	v_cvt_pk_bf16_f32 v57, v185, v187
	v_cvt_pk_bf16_f32 v58, v181, v183
	s_waitcnt lgkmcnt(1)
	v_mfma_f32_32x32x16_bf16 v[96:111], v[48:51], v[112:115], v[96:111]
	v_cvt_pk_bf16_f32 v59, v180, v182
	v_cvt_pk_bf16_f32 v52, v64, v65
	v_cvt_pk_bf16_f32 v53, v66, v67
	v_cvt_pk_bf16_f32 v54, v68, v69
	v_cvt_pk_bf16_f32 v55, v70, v71
	v_cvt_pk_bf16_f32 v48, v72, v73
	v_cvt_pk_bf16_f32 v49, v74, v75
	s_waitcnt lgkmcnt(0)
	v_mfma_f32_32x32x16_bf16 v[80:95], v[236:239], v[112:115], v[80:95]
	v_cvt_pk_bf16_f32 v50, v76, v77
	v_cvt_pk_bf16_f32 v51, v78, v79
	s_add_i32 s42, s89, 0xffffc000
	s_and_b32 s42, s42, 0xc000
	s_add_i32 s43, s85, s42
	s_cmp_lt_u32 s90, 29
	s_cselect_b64 s[44:45], -1, 0
	s_cmp_gt_u32 s90, 28
	s_cselect_b64 s[42:43], -1, 0
	s_and_b64 vcc, exec, s[42:43]
	s_waitcnt vmcnt(2)
	ds_write_b128 v204, v[144:147] offset:16384
	s_waitcnt vmcnt(1)
	ds_write_b128 v249, v[148:151] offset:16384
	s_waitcnt vmcnt(0)
	ds_write_b64 v250, v[174:175] offset:16384
	s_cbranch_vccnz .Lf2_741
	global_load_dwordx4 v[136:139], v240, s[98:99]
	global_load_dwordx4 v[140:143], v241, s[98:99]
	global_load_dwordx2 v[172:173], v242, s[100:101]
	s_add_u32 s98, s98, 0x10000
	s_addc_u32 s99, s99, 0
	s_add_u32 s100, s100, 0x1000
	s_addc_u32 s101, s101, 0
; __device__ __forceinline__ s16x4 vtr(lds_cptr p) { return __builtin_bit_cast(s16x4, __builtin_amdgcn_ds_read_tr16_b64_v4i16((LAS v4i16_t*)p)); }
; template <bool FIRST> __device__ __forceinline__ void partialSM(f32x16& p0, f32x16& p1, float& mref, f32x16& negm, float& alpha) {
;   constexpr float THRL = THR * 1.4426950408889634f;
;   float pmax = p0[0];
; #pragma unroll
;   for (int r = 1; r < 16; ++r) pmax = fmaxf(pmax, p0[r]);
; #pragma unroll
;   for (int r = 0; r < 16; ++r) pmax = fmaxf(pmax, p1[r]);
;   { auto rr = __builtin_amdgcn_permlane32_swap(__float_as_uint(pmax), __float_as_uint(pmax), false, false);
;     pmax = fmaxf(__uint_as_float(rr[0]), __uint_as_float(rr[1])); }
;   if (!FIRST && __builtin_expect(__all(pmax <= THRL), 1)) { alpha = 1.f; }
; template <int D0> __device__ __forceinline__ void pv_one(f32x16& od, lds_cptr vp, bf16x8 pa0, bf16x8 pa1, bf16x8 pa2, bf16x8 pa3) {
;   const s16x4 l0 = vtr(vp + v_rd_off(D0, 0, 0)), h0 = vtr(vp + v_rd_off(D0, 0, 1)), l1 = vtr(vp + v_rd_off(D0, 1, 0)), h1 = vtr(vp + v_rd_off(D0, 1, 1));
;   const s16x4 l2 = vtr(vp + v_rd_off(D0, 2, 0)), h2 = vtr(vp + v_rd_off(D0, 2, 1)), l3 = vtr(vp + v_rd_off(D0, 3, 0)), h3 = vtr(vp + v_rd_off(D0, 3, 1));
;     ...
;   od = __builtin_amdgcn_mfma_f32_32x32x16_bf16(pa0, PK(l0, h0), od, 0, 0, 0);
;   od = __builtin_amdgcn_mfma_f32_32x32x16_bf16(pa1, PK(l1, h1), od, 0, 0, 0);
;   od = __builtin_amdgcn_mfma_f32_32x32x16_bf16(pa2, PK(l2, h2), od, 0, 0, 0);
;   od = __builtin_amdgcn_mfma_f32_32x32x16_bf16(pa3, PK(l3, h3), od, 0, 0, 0);
;     ...
; }
; __device__ __forceinline__ void pv_d0(f32x16* o, lds_cptr vp, bf16x8 pa0, bf16x8 pa1, bf16x8 pa2, bf16x8 pa3) {
;   pv_one<0>(o[0], vp, pa0, pa1, pa2, pa3); pv_one<1>(o[1], vp, pa0, pa1, pa2, pa3);
; }
.Lf2_741:
	s_and_b32 s48, s89, 0xc000
	ds_read_b64_tr_b16 v[64:65], v203 offset:32768
	ds_read_b64_tr_b16 v[66:67], v203 offset:34816
	ds_read_b64_tr_b16 v[70:71], v203 offset:35328
	ds_read_b64_tr_b16 v[68:69], v203 offset:33280
	s_waitcnt lgkmcnt(2)
	v_mfma_f32_32x32x16_bf16 v[0:15], v[60:63], v[64:67], v[0:15]
	ds_read_b64_tr_b16 v[64:65], v203 offset:36864
	ds_read_b64_tr_b16 v[66:67], v203 offset:38912
	ds_read_b64_tr_b16 v[74:75], v203 offset:39424
	ds_read_b64_tr_b16 v[72:73], v203 offset:37376
	s_waitcnt lgkmcnt(2)
	v_mfma_f32_32x32x16_bf16 v[0:15], v[56:59], v[64:67], v[0:15]
	ds_read_b64_tr_b16 v[64:65], v203 offset:40960
	ds_read_b64_tr_b16 v[66:67], v203 offset:43008
	ds_read_b64_tr_b16 v[78:79], v203 offset:43520
	ds_read_b64_tr_b16 v[76:77], v203 offset:41472
	v_mfma_f32_32x32x16_bf16 v[16:31], v[60:63], v[68:71], v[16:31]
	s_waitcnt lgkmcnt(2)
	v_mfma_f32_32x32x16_bf16 v[0:15], v[52:55], v[64:67], v[0:15]
	ds_read_b64_tr_b16 v[64:65], v203 offset:45056
	ds_read_b64_tr_b16 v[66:67], v203 offset:47104
	ds_read_b64_tr_b16 v[186:187], v203 offset:47616
	ds_read_b64_tr_b16 v[184:185], v203 offset:45568
	v_mfma_f32_32x32x16_bf16 v[16:31], v[56:59], v[72:75], v[16:31]
	s_waitcnt lgkmcnt(2)
	v_mfma_f32_32x32x16_bf16 v[0:15], v[48:51], v[64:67], v[0:15]
	v_max_f32_e32 v64, v97, v97
	v_max_f32_e32 v65, v96, v96
	v_max_f32_e32 v64, v65, v64
	v_max3_f32 v64, v64, v98, v99
	v_max3_f32 v60, v64, v100, v101
	v_max3_f32 v60, v60, v102, v103
	v_max3_f32 v60, v60, v104, v105
	v_max3_f32 v60, v60, v106, v107
	v_max3_f32 v60, v60, v108, v109
	v_mfma_f32_32x32x16_bf16 v[16:31], v[52:55], v[76:79], v[16:31]
	v_max3_f32 v60, v60, v110, v111
	v_max3_f32 v60, v60, v80, v81
	v_max3_f32 v56, v60, v82, v83
	v_max3_f32 v56, v56, v84, v85
	v_max3_f32 v56, v56, v86, v87
	v_max3_f32 v56, v56, v88, v89
	v_max3_f32 v56, v56, v90, v91
	v_max3_f32 v56, v56, v92, v93
	s_waitcnt lgkmcnt(0)
	v_mfma_f32_32x32x16_bf16 v[16:31], v[48:51], v[184:187], v[16:31]
	v_max3_f32 v56, v56, v94, v95
	v_mov_b32_e32 v52, v56
	s_nop 1
	v_permlane32_swap_b32_e32 v56, v52
	v_max_f32_e32 v52, v52, v52
	v_max_f32_e32 v53, v56, v56
	v_max_f32_e32 v52, v53, v52
	v_cmp_ge_f32_e32 vcc, s86, v52
	s_cmp_eq_u64 vcc, exec
	s_cbranch_scc0 .Lf2_757
	v_mov_b32_e32 v169, 1.0
	v_cmp_gt_f32_e32 vcc, 1.0, v169
	s_cbranch_vccz .Lf2_746

; #define SBAR() __builtin_amdgcn_sched_barrier(0)
; #define PK4(P, BASE, OUT) do { u32x4 w = {cvt_pk_bf16(P[BASE + 0], P[BASE + 1]), cvt_pk_bf16(P[BASE + 2], P[BASE + 3]), cvt_pk_bf16(P[BASE + 4], P[BASE + 5]), cvt_pk_bf16(P[BASE + 6], P[BASE + 7])}; \
;     OUT = *reinterpret_cast<bf16x8*>(&w); } while (0)
; #define SLOAD(i, k0) do { const bf16_t* vt_ = Vh + (size_t)(k0) * 512; const bf16_t* kt_ = KNh + (size_t)(k0) * 512; const bf16_t* rt_ = KRb + (size_t)(k0) * 32; \
;     sr_[i].vs = *reinterpret_cast<const bf16x8*>(vt_ + lo_kv); sr_[i].ks = *reinterpret_cast<const bf16x8*>(kt_ + lo_kv); sr_[i].kr = *reinterpret_cast<const s16x4*>(rt_ + lo_kr); } while (0)
; __device__ __forceinline__ void finishSM(f32x16& p0, f32x16& p1, float alpha, float& l_reg, bf16x8& pa0, bf16x8& pa1, bf16x8& pa2, bf16x8& pa3) {
; #pragma unroll
;   for (int r = 0; r < 16; ++r) p1[r] = __builtin_amdgcn_exp2f(p1[r]);
;   float ps = 0;
; #pragma unroll
;   for (int r = 0; r < 16; ++r) ps += p0[r];
; #pragma unroll
;   for (int r = 0; r < 16; ++r) ps += p1[r];
;   { auto rr = __builtin_amdgcn_permlane32_swap(__float_as_uint(ps), __float_as_uint(ps), false, false);
;     ps = __uint_as_float(rr[0]) + __uint_as_float(rr[1]); }
;   l_reg = l_reg * alpha + ps;
;     ...
;   PK4(p0, 0, pa0); PK4(p0, 8, pa1); PK4(p1, 0, pa2); PK4(p1, 8, pa3);
;     ...
; }
; __device__ __forceinline__ void qkt(f32x16& p0, f32x16& p1, const char* Ks, const bf16x8* qr, const f32x16& negm, int r32, int hi) {
;   p0 = negm; p1 = negm;
; #pragma unroll
;   for (int d0 = 0; d0 < 6; ++d0) { int cb = (d0 * 16 + hi * 8) * 2;
;     bf16x8 b0 = *reinterpret_cast<const bf16x8*>(Ks + KSWZ(r32, cb));
;     bf16x8 b1 = *reinterpret_cast<const bf16x8*>(Ks + KSWZ(32 + r32, cb));
;     p0 = __builtin_amdgcn_mfma_f32_32x32x16_bf16(b0, qr[d0], p0, 0, 0, 0);
;     p1 = __builtin_amdgcn_mfma_f32_32x32x16_bf16(b1, qr[d0], p1, 0, 0, 0); }
; }
; __device__ __forceinline__ void attn_unit(const bf16_t* __restrict__ Qb, const bf16_t* __restrict__ KNh, const bf16_t* __restrict__ KRb, const bf16_t* __restrict__ Vh, bf16_t* __restrict__ Ob, char* lds) {
;     ...
;     SBAR(); qkt(pA0, pA1, K_lds + ((j + 1) & 3) * SHM_K, qr, negm, r32, hi);
;     finishSM(pB0, pB1, alB, l_reg, pa0, pa1, pa2, pa3); SBAR();
;     if (j + 3 < NT) { SWRITE((j + 3) & 3, 0); } if (j + 4 < NT) { SLOAD(1, (j + 4) * KVBLK); } SBAR();
.Lf2_746:
	s_waitcnt lgkmcnt(0)
	s_barrier
	v_exp_f32_e32 v192, v96
	v_exp_f32_e32 v193, v97
	v_exp_f32_e32 v194, v98
	v_exp_f32_e32 v195, v99
	v_exp_f32_e32 v216, v100
	v_exp_f32_e32 v217, v101
	v_exp_f32_e32 v219, v102
	v_exp_f32_e32 v220, v103
	v_exp_f32_e32 v221, v104
	v_exp_f32_e32 v222, v105
	v_exp_f32_e32 v223, v106
	v_exp_f32_e32 v224, v107
	v_exp_f32_e32 v225, v108
	v_exp_f32_e32 v226, v109
	v_exp_f32_e32 v227, v110
	v_exp_f32_e32 v228, v111
	s_add_i32 s46, s89, 0xffff8000
	s_and_b32 s46, s46, 0xc000
	s_add_i32 s46, s46, 0
	s_add_i32 s46, s46, 0x10000
	ds_read_b128 v[64:67], v243
	ds_read_b128 v[184:187], v243 offset:8192
	v_exp_f32_e32 v80, v80
	v_exp_f32_e32 v81, v81
	s_waitcnt lgkmcnt(1)
	v_mfma_f32_32x32x16_bf16 v[96:111], v[64:67], v[132:135], v[32:47]
	v_exp_f32_e32 v82, v82
	v_exp_f32_e32 v83, v83
	v_exp_f32_e32 v87, v87
	v_exp_f32_e32 v229, v92
	v_exp_f32_e32 v230, v93
	v_exp_f32_e32 v231, v94
	v_exp_f32_e32 v232, v95
	s_waitcnt lgkmcnt(0)
	v_mfma_f32_32x32x16_bf16 v[64:79], v[184:187], v[132:135], v[32:47]
	ds_read_b128 v[184:187], v244
	ds_read_b128 v[188:191], v244 offset:8192
	s_waitcnt lgkmcnt(1)
	v_mfma_f32_32x32x16_bf16 v[96:111], v[184:187], v[128:131], v[96:111]
	s_waitcnt lgkmcnt(0)
	v_mfma_f32_32x32x16_bf16 v[64:79], v[188:191], v[128:131], v[64:79]
	ds_read_b128 v[184:187], v245
	ds_read_b128 v[188:191], v245 offset:8192
	s_waitcnt lgkmcnt(1)
	v_mfma_f32_32x32x16_bf16 v[96:111], v[184:187], v[124:127], v[96:111]
	s_waitcnt lgkmcnt(0)
	v_mfma_f32_32x32x16_bf16 v[64:79], v[188:191], v[124:127], v[64:79]
	ds_read_b128 v[184:187], v246
	ds_read_b128 v[188:191], v246 offset:8192
	s_waitcnt lgkmcnt(1)
	v_mfma_f32_32x32x16_bf16 v[96:111], v[184:187], v[120:123], v[96:111]
	s_waitcnt lgkmcnt(0)
	v_mfma_f32_32x32x16_bf16 v[64:79], v[188:191], v[120:123], v[64:79]
	ds_read_b128 v[184:187], v247
	ds_read_b128 v[188:191], v247 offset:8192
	s_waitcnt lgkmcnt(1)
	v_mfma_f32_32x32x16_bf16 v[96:111], v[184:187], v[116:119], v[96:111]
	s_waitcnt lgkmcnt(0)
	v_mfma_f32_32x32x16_bf16 v[64:79], v[188:191], v[116:119], v[64:79]
	ds_read_b128 v[184:187], v248
	ds_read_b128 v[188:191], v248 offset:8192
	v_cvt_pk_bf16_f32 v92, v192, v193
	v_cvt_pk_bf16_f32 v93, v194, v195
	v_cvt_pk_bf16_f32 v94, v216, v217
	v_cvt_pk_bf16_f32 v95, v219, v220
	s_waitcnt lgkmcnt(1)
	v_mfma_f32_32x32x16_bf16 v[96:111], v[184:187], v[112:115], v[96:111]
	v_exp_f32_e32 v185, v84
	v_fma_f32 v84, v165, v169, v192
	v_add_f32_e32 v84, v193, v84
	v_add_f32_e32 v84, v194, v84
	v_add_f32_e32 v84, v195, v84
	v_add_f32_e32 v84, v216, v84
	v_add_f32_e32 v84, v217, v84
	v_add_f32_e32 v84, v219, v84
	v_add_f32_e32 v84, v220, v84
	v_add_f32_e32 v84, v221, v84
	v_add_f32_e32 v84, v222, v84
	v_add_f32_e32 v84, v223, v84
	v_add_f32_e32 v84, v224, v84
	v_add_f32_e32 v84, v225, v84
	v_add_f32_e32 v84, v226, v84
	v_add_f32_e32 v84, v227, v84
	v_add_f32_e32 v84, v228, v84
	v_add_f32_e32 v84, v80, v84
	v_exp_f32_e32 v186, v85
	v_add_f32_e32 v84, v81, v84
	v_exp_f32_e32 v187, v86
	v_add_f32_e32 v84, v82, v84
	v_add_f32_e32 v84, v83, v84
	s_waitcnt lgkmcnt(0)
	v_mfma_f32_32x32x16_bf16 v[64:79], v[188:191], v[112:115], v[64:79]
	v_exp_f32_e32 v188, v88
	v_add_f32_e32 v84, v185, v84
	v_exp_f32_e32 v189, v89
	v_add_f32_e32 v84, v186, v84
	v_exp_f32_e32 v190, v90
	v_add_f32_e32 v84, v187, v84
	v_exp_f32_e32 v191, v91
	v_add_f32_e32 v84, v87, v84
	v_add_f32_e32 v84, v188, v84
	v_add_f32_e32 v84, v189, v84
	v_add_f32_e32 v84, v190, v84
	v_add_f32_e32 v84, v191, v84
	v_add_f32_e32 v84, v229, v84
	v_add_f32_e32 v84, v230, v84
	v_add_f32_e32 v84, v231, v84
	v_add_f32_e32 v152, v232, v84
	v_cvt_pk_bf16_f32 v88, v221, v222
	v_cvt_pk_bf16_f32 v89, v223, v224
	v_cvt_pk_bf16_f32 v90, v225, v226
	v_cvt_pk_bf16_f32 v91, v227, v228
	v_cvt_pk_bf16_f32 v84, v80, v81
	v_cvt_pk_bf16_f32 v85, v82, v83
	v_cvt_pk_bf16_f32 v86, v185, v186
	v_cvt_pk_bf16_f32 v87, v187, v87
	v_cvt_pk_bf16_f32 v80, v188, v189
	v_cvt_pk_bf16_f32 v81, v190, v191
	v_cvt_pk_bf16_f32 v82, v229, v230
	v_cvt_pk_bf16_f32 v83, v231, v232
	s_andn2_b64 vcc, exec, s[44:45]
	s_cbranch_vccnz .Lf2_748
	s_add_i32 s44, s48, 0
	s_add_i32 s44, s44, 0x10000
	s_waitcnt vmcnt(2)
	ds_write_b128 v204, v[136:139] offset:32768
	s_waitcnt vmcnt(1)
	ds_write_b128 v249, v[140:143] offset:32768
	s_waitcnt vmcnt(0)
	ds_write_b64 v250, v[172:173] offset:32768

; __device__ __forceinline__ s16x4 vtr(lds_cptr p) { return __builtin_bit_cast(s16x4, __builtin_amdgcn_ds_read_tr16_b64_v4i16((LAS v4i16_t*)p)); }
; template <bool FIRST> __device__ __forceinline__ void partialSM(f32x16& p0, f32x16& p1, float& mref, f32x16& negm, float& alpha) {
;   constexpr float THRL = THR * 1.4426950408889634f;
;   float pmax = p0[0];
; #pragma unroll
;   for (int r = 1; r < 16; ++r) pmax = fmaxf(pmax, p0[r]);
; #pragma unroll
;   for (int r = 0; r < 16; ++r) pmax = fmaxf(pmax, p1[r]);
;   { auto rr = __builtin_amdgcn_permlane32_swap(__float_as_uint(pmax), __float_as_uint(pmax), false, false);
;     pmax = fmaxf(__uint_as_float(rr[0]), __uint_as_float(rr[1])); }
;   if (!FIRST && __builtin_expect(__all(pmax <= THRL), 1)) { alpha = 1.f; }
; template <int D0> __device__ __forceinline__ void pv_one(f32x16& od, lds_cptr vp, bf16x8 pa0, bf16x8 pa1, bf16x8 pa2, bf16x8 pa3) {
;   const s16x4 l0 = vtr(vp + v_rd_off(D0, 0, 0)), h0 = vtr(vp + v_rd_off(D0, 0, 1)), l1 = vtr(vp + v_rd_off(D0, 1, 0)), h1 = vtr(vp + v_rd_off(D0, 1, 1));
;   const s16x4 l2 = vtr(vp + v_rd_off(D0, 2, 0)), h2 = vtr(vp + v_rd_off(D0, 2, 1)), l3 = vtr(vp + v_rd_off(D0, 3, 0)), h3 = vtr(vp + v_rd_off(D0, 3, 1));
;     ...
;   od = __builtin_amdgcn_mfma_f32_32x32x16_bf16(pa0, PK(l0, h0), od, 0, 0, 0);
;   od = __builtin_amdgcn_mfma_f32_32x32x16_bf16(pa1, PK(l1, h1), od, 0, 0, 0);
;   od = __builtin_amdgcn_mfma_f32_32x32x16_bf16(pa2, PK(l2, h2), od, 0, 0, 0);
;   od = __builtin_amdgcn_mfma_f32_32x32x16_bf16(pa3, PK(l3, h3), od, 0, 0, 0);
;     ...
; }
; __device__ __forceinline__ void pv_d0(f32x16* o, lds_cptr vp, bf16x8 pa0, bf16x8 pa1, bf16x8 pa2, bf16x8 pa3) {
;   pv_one<0>(o[0], vp, pa0, pa1, pa2, pa3); pv_one<1>(o[1], vp, pa0, pa1, pa2, pa3);
; }
.Lf2_750:
	ds_read_b64_tr_b16 v[180:181], v203 offset:49152
	ds_read_b64_tr_b16 v[182:183], v203 offset:51200
	ds_read_b64_tr_b16 v[188:189], v203 offset:51712
	ds_read_b64_tr_b16 v[186:187], v203 offset:49664
	s_waitcnt lgkmcnt(2)
	v_mfma_f32_32x32x16_bf16 v[0:15], v[92:95], v[180:183], v[0:15]
	ds_read_b64_tr_b16 v[180:181], v203 offset:53248
	ds_read_b64_tr_b16 v[182:183], v203 offset:55296
	ds_read_b64_tr_b16 v[192:193], v203 offset:55808
	ds_read_b64_tr_b16 v[190:191], v203 offset:53760
	s_waitcnt lgkmcnt(2)
	v_mfma_f32_32x32x16_bf16 v[0:15], v[88:91], v[180:183], v[0:15]
	ds_read_b64_tr_b16 v[180:181], v203 offset:57344
	ds_read_b64_tr_b16 v[182:183], v203 offset:59392
	ds_read_b64_tr_b16 v[222:223], v203 offset:59904
	ds_read_b64_tr_b16 v[220:221], v203 offset:57856
	v_mfma_f32_32x32x16_bf16 v[16:31], v[92:95], v[186:189], v[16:31]
	s_waitcnt lgkmcnt(2)
	v_mfma_f32_32x32x16_bf16 v[0:15], v[84:87], v[180:183], v[0:15]
	ds_read_b64_tr_b16 v[180:181], v203 offset:61440
	ds_read_b64_tr_b16 v[182:183], v203 offset:63488
	ds_read_b64_tr_b16 v[226:227], v203 offset:64000
	ds_read_b64_tr_b16 v[224:225], v203 offset:61952
	v_mfma_f32_32x32x16_bf16 v[16:31], v[88:91], v[190:193], v[16:31]
	s_waitcnt lgkmcnt(2)
	v_mfma_f32_32x32x16_bf16 v[0:15], v[80:83], v[180:183], v[0:15]
	v_max_f32_e32 v180, v97, v97
	v_max_f32_e32 v181, v96, v96
	v_max_f32_e32 v180, v181, v180
	v_max3_f32 v180, v180, v98, v99
	v_max3_f32 v180, v180, v100, v101
	v_max3_f32 v92, v180, v102, v103
	v_max3_f32 v92, v92, v104, v105
	v_max3_f32 v92, v92, v106, v107
	v_max3_f32 v92, v92, v108, v109
	v_mfma_f32_32x32x16_bf16 v[16:31], v[84:87], v[220:223], v[16:31]
	v_max3_f32 v92, v92, v110, v111
	v_max3_f32 v92, v92, v64, v65
	v_max3_f32 v92, v92, v66, v67
	v_max3_f32 v88, v92, v68, v69
	v_max3_f32 v88, v88, v70, v71
	v_max3_f32 v88, v88, v72, v73
	v_max3_f32 v88, v88, v74, v75
	v_max3_f32 v88, v88, v76, v77
	s_waitcnt lgkmcnt(0)
	v_mfma_f32_32x32x16_bf16 v[16:31], v[80:83], v[224:227], v[16:31]
	v_max3_f32 v88, v88, v78, v79
	v_mov_b32_e32 v89, v88
	s_nop 1
	v_permlane32_swap_b32_e32 v88, v89
	v_max_f32_e32 v84, v89, v89
	v_max_f32_e32 v85, v88, v88
	v_max_f32_e32 v85, v85, v84
	v_cmp_ge_f32_e32 vcc, s86, v85
	s_cmp_eq_u64 vcc, exec
	v_mov_b32_e32 v84, 1.0
	s_cbranch_scc0 .Lf2_758
	v_cmp_gt_f32_e32 vcc, 1.0, v84
	s_cbranch_vccz .Lf2_755

; #define SBAR() __builtin_amdgcn_sched_barrier(0)
; #define ABAR() asm volatile("s_waitcnt lgkmcnt(0)\n\ts_barrier" ::: "memory")
; #define SLOAD(i, k0) do { const bf16_t* vt_ = Vh + (size_t)(k0) * 512; const bf16_t* kt_ = KNh + (size_t)(k0) * 512; const bf16_t* rt_ = KRb + (size_t)(k0) * 32; \
;     sr_[i].vs = *reinterpret_cast<const bf16x8*>(vt_ + lo_kv); sr_[i].ks = *reinterpret_cast<const bf16x8*>(kt_ + lo_kv); sr_[i].kr = *reinterpret_cast<const s16x4*>(rt_ + lo_kr); } while (0)
; #define SWRITE(slot, i) do { *(bf16x8*)(V_lds + (slot) * SHM_V + vst) = sr_[i].vs; *(bf16x8*)(K_lds + (slot) * SHM_K + kst) = sr_[i].ks; *(s16x4*)(K_lds + (slot) * SHM_K + krst) = sr_[i].kr; } while (0)
; #define RESC(a) do { if (__any((a) < 1.f)) { if (hi == 0) al_l[r32] = (a); asm volatile("s_waitcnt lgkmcnt(0)" ::: "memory"); \
;     _Pragma("unroll") for (int d = 0; d < 2; ++d) _Pragma("unroll") for (int r = 0; r < 16; ++r) o[d][r] *= al_l[crow(r, hi)]; } } while (0)
; __device__ __forceinline__ void qkt(f32x16& p0, f32x16& p1, const char* Ks, const bf16x8* qr, const f32x16& negm, int r32, int hi) {
;   p0 = negm; p1 = negm;
; #pragma unroll
;   for (int d0 = 0; d0 < 6; ++d0) { int cb = (d0 * 16 + hi * 8) * 2;
;     bf16x8 b0 = *reinterpret_cast<const bf16x8*>(Ks + KSWZ(r32, cb));
;     bf16x8 b1 = *reinterpret_cast<const bf16x8*>(Ks + KSWZ(32 + r32, cb));
;     p0 = __builtin_amdgcn_mfma_f32_32x32x16_bf16(b0, qr[d0], p0, 0, 0, 0);
;     p1 = __builtin_amdgcn_mfma_f32_32x32x16_bf16(b1, qr[d0], p1, 0, 0, 0); }
; }
; __device__ __forceinline__ void attn_unit(const bf16_t* __restrict__ Qb, const bf16_t* __restrict__ KNh, const bf16_t* __restrict__ KRb, const bf16_t* __restrict__ Vh, bf16_t* __restrict__ Ob, char* lds) {
;     ...
;   for (int j = 1; j + 1 < NT; j += 2) {
;     SBAR(); qkt(pB0, pB1, K_lds + (j & 3) * SHM_K, qr, negm, r32, hi);
;     finishSM(pA0, pA1, alA, l_reg, pa0, pa1, pa2, pa3); SBAR();
;     if (j + 2 < NT) { SWRITE((j + 2) & 3, 1); } if (j + 3 < NT) { SLOAD(0, (j + 3) * KVBLK); } SBAR();
;     pv_d0(o, vb0 + ((j - 1) & 3) * SHM_V, pa0, pa1, pa2, pa3); partialSM<false>(pB0, pB1, mref, negm, alB);
;     RESC(alB); ABAR();
.Lf2_755:
	v_exp_f32_e32 v194, v96
	v_exp_f32_e32 v216, v97
	v_exp_f32_e32 v192, v98
	v_exp_f32_e32 v195, v99
	v_exp_f32_e32 v190, v100
	v_exp_f32_e32 v193, v101
	v_exp_f32_e32 v189, v102
	v_exp_f32_e32 v191, v103
	v_exp_f32_e32 v186, v104
	v_exp_f32_e32 v188, v105
	v_exp_f32_e32 v185, v106
	v_exp_f32_e32 v187, v107
	v_exp_f32_e32 v181, v108
	v_exp_f32_e32 v183, v109
	v_exp_f32_e32 v180, v110
	v_exp_f32_e32 v182, v111
	s_waitcnt lgkmcnt(0)
	s_barrier
	s_add_i32 s90, s90, 2
	s_add_i32 s89, s89, 0x8000
	s_cmp_lt_u32 s90, 26
	v_mov_b32_e32 v163, v84
	s_cbranch_scc1 .Lattn_f4
.LBB0_739:
	s_add_i32 s41, s89, 0xffff4000
	s_and_b32 s41, s41, 0xc000
	s_add_i32 s42, s85, s41
	v_add_u32_e32 v52, s42, v206
	ds_read_b128 v[48:51], v52
	ds_read_b128 v[52:55], v52 offset:8192
	v_add_u32_e32 v56, s42, v207
	v_add_u32_e32 v60, s42, v208
	v_add_u32_e32 v165, s42, v209
	s_waitcnt lgkmcnt(1)
	v_mfma_f32_32x32x16_bf16 v[96:111], v[48:51], v[132:135], v[32:47]
	ds_read_b128 v[48:51], v56
	ds_read_b128 v[56:59], v56 offset:8192
	v_add_u32_e32 v167, s42, v210
	v_exp_f32_e32 v64, v64
	v_exp_f32_e32 v65, v65
	v_exp_f32_e32 v66, v66
	v_exp_f32_e32 v67, v67
	v_exp_f32_e32 v68, v68
	s_waitcnt lgkmcnt(2)
	v_mfma_f32_32x32x16_bf16 v[80:95], v[52:55], v[132:135], v[32:47]
	ds_read_b128 v[52:55], v60
	ds_read_b128 v[60:63], v60 offset:8192
	ds_read_b128 v[220:223], v165
	ds_read_b128 v[224:227], v165 offset:8192
	ds_read_b128 v[228:231], v167
	ds_read_b128 v[232:235], v167 offset:8192
	v_exp_f32_e32 v69, v69
	v_exp_f32_e32 v70, v70
	v_exp_f32_e32 v71, v71
	v_add_u32_e32 v169, s42, v211
	v_exp_f32_e32 v72, v72
	v_exp_f32_e32 v73, v73
	s_waitcnt lgkmcnt(7)
	v_mfma_f32_32x32x16_bf16 v[96:111], v[48:51], v[128:131], v[96:111]
	ds_read_b128 v[48:51], v169
	ds_read_b128 v[236:239], v169 offset:8192
	v_exp_f32_e32 v74, v74
	v_exp_f32_e32 v75, v75
	v_exp_f32_e32 v76, v76
	v_exp_f32_e32 v77, v77
	v_exp_f32_e32 v78, v78
	v_exp_f32_e32 v79, v79
	s_waitcnt lgkmcnt(8)
	v_mfma_f32_32x32x16_bf16 v[80:95], v[56:59], v[128:131], v[80:95]
	s_waitcnt lgkmcnt(7)
	v_mfma_f32_32x32x16_bf16 v[96:111], v[52:55], v[124:127], v[96:111]
	v_fma_f32 v52, v163, v152, v194
	v_add_f32_e32 v52, v216, v52
	v_add_f32_e32 v52, v192, v52
	v_add_f32_e32 v52, v195, v52
	v_add_f32_e32 v52, v190, v52
	v_add_f32_e32 v52, v193, v52
	v_add_f32_e32 v52, v189, v52
	s_waitcnt lgkmcnt(6)
	v_mfma_f32_32x32x16_bf16 v[80:95], v[60:63], v[124:127], v[80:95]
	v_add_f32_e32 v52, v191, v52
	v_add_f32_e32 v52, v186, v52
	v_add_f32_e32 v52, v188, v52
	v_add_f32_e32 v52, v185, v52
	v_add_f32_e32 v52, v187, v52
	v_add_f32_e32 v52, v181, v52
	v_add_f32_e32 v52, v183, v52
	s_waitcnt lgkmcnt(5)
	v_mfma_f32_32x32x16_bf16 v[96:111], v[220:223], v[120:123], v[96:111]
	v_add_f32_e32 v52, v180, v52
	v_add_f32_e32 v52, v182, v52
	v_add_f32_e32 v52, v64, v52
	v_add_f32_e32 v52, v65, v52
	v_add_f32_e32 v52, v66, v52
	v_add_f32_e32 v52, v67, v52
	v_add_f32_e32 v52, v68, v52
	s_waitcnt lgkmcnt(4)
	v_mfma_f32_32x32x16_bf16 v[80:95], v[224:227], v[120:123], v[80:95]
	v_add_f32_e32 v52, v69, v52
	v_add_f32_e32 v52, v70, v52
	v_add_f32_e32 v52, v71, v52
	v_add_f32_e32 v52, v72, v52
	v_add_f32_e32 v52, v73, v52
	v_add_f32_e32 v52, v74, v52
	v_add_f32_e32 v52, v75, v52
	s_waitcnt lgkmcnt(3)
	v_mfma_f32_32x32x16_bf16 v[96:111], v[228:231], v[116:119], v[96:111]
	v_add_f32_e32 v52, v76, v52
	v_add_f32_e32 v52, v77, v52
	v_add_f32_e32 v52, v78, v52
	v_add_f32_e32 v165, v79, v52
	s_waitcnt lgkmcnt(2)
	v_mfma_f32_32x32x16_bf16 v[80:95], v[232:235], v[116:119], v[80:95]
	v_cvt_pk_bf16_f32 v60, v194, v216
	v_cvt_pk_bf16_f32 v61, v192, v195
	v_cvt_pk_bf16_f32 v62, v190, v193
	v_cvt_pk_bf16_f32 v63, v189, v191
	v_cvt_pk_bf16_f32 v56, v186, v188
	v_cvt_pk_bf16_f32 v57, v185, v187
	v_cvt_pk_bf16_f32 v58, v181, v183
	s_waitcnt lgkmcnt(1)
	v_mfma_f32_32x32x16_bf16 v[96:111], v[48:51], v[112:115], v[96:111]
	v_cvt_pk_bf16_f32 v59, v180, v182
	v_cvt_pk_bf16_f32 v52, v64, v65
	v_cvt_pk_bf16_f32 v53, v66, v67
	v_cvt_pk_bf16_f32 v54, v68, v69
	v_cvt_pk_bf16_f32 v55, v70, v71
	v_cvt_pk_bf16_f32 v48, v72, v73
	v_cvt_pk_bf16_f32 v49, v74, v75
	s_waitcnt lgkmcnt(0)
	v_mfma_f32_32x32x16_bf16 v[80:95], v[236:239], v[112:115], v[80:95]
	v_cvt_pk_bf16_f32 v50, v76, v77
	v_cvt_pk_bf16_f32 v51, v78, v79
	s_add_i32 s42, s89, 0xffffc000
	s_and_b32 s42, s42, 0xc000
	s_add_i32 s43, s85, s42
	s_cmp_lt_u32 s90, 29
	s_cselect_b64 s[44:45], -1, 0
	s_cmp_gt_u32 s90, 28
	v_add_u32_e32 v64, s43, v202
	v_add_u32_e32 v65, s43, v201
	v_add_u32_e32 v66, s42, v204
	s_cselect_b64 s[42:43], -1, 0
	s_and_b64 vcc, exec, s[42:43]
	s_waitcnt vmcnt(2)
	ds_write_b128 v66, v[144:147]
	s_waitcnt vmcnt(1)
	ds_write_b128 v65, v[148:151]
	s_waitcnt vmcnt(0)
	ds_write_b64 v64, v[174:175]
	s_cbranch_vccnz .LBB0_741
	global_load_dwordx4 v[136:139], v240, s[98:99]
	global_load_dwordx4 v[140:143], v241, s[98:99]
	global_load_dwordx2 v[172:173], v242, s[100:101]
	s_add_u32 s98, s98, 0x10000
	s_addc_u32 s99, s99, 0
	s_add_u32 s100, s100, 0x1000
	s_addc_u32 s101, s101, 0

; #define SBAR() __builtin_amdgcn_sched_barrier(0)
; #define PK4(P, BASE, OUT) do { u32x4 w = {cvt_pk_bf16(P[BASE + 0], P[BASE + 1]), cvt_pk_bf16(P[BASE + 2], P[BASE + 3]), cvt_pk_bf16(P[BASE + 4], P[BASE + 5]), cvt_pk_bf16(P[BASE + 6], P[BASE + 7])}; \
;     OUT = *reinterpret_cast<bf16x8*>(&w); } while (0)
; #define SLOAD(i, k0) do { const bf16_t* vt_ = Vh + (size_t)(k0) * 512; const bf16_t* kt_ = KNh + (size_t)(k0) * 512; const bf16_t* rt_ = KRb + (size_t)(k0) * 32; \
;     sr_[i].vs = *reinterpret_cast<const bf16x8*>(vt_ + lo_kv); sr_[i].ks = *reinterpret_cast<const bf16x8*>(kt_ + lo_kv); sr_[i].kr = *reinterpret_cast<const s16x4*>(rt_ + lo_kr); } while (0)
; __device__ __forceinline__ void finishSM(f32x16& p0, f32x16& p1, float alpha, float& l_reg, bf16x8& pa0, bf16x8& pa1, bf16x8& pa2, bf16x8& pa3) {
; #pragma unroll
;   for (int r = 0; r < 16; ++r) p1[r] = __builtin_amdgcn_exp2f(p1[r]);
;   float ps = 0;
; #pragma unroll
;   for (int r = 0; r < 16; ++r) ps += p0[r];
; #pragma unroll
;   for (int r = 0; r < 16; ++r) ps += p1[r];
;   { auto rr = __builtin_amdgcn_permlane32_swap(__float_as_uint(ps), __float_as_uint(ps), false, false);
;     ps = __uint_as_float(rr[0]) + __uint_as_float(rr[1]); }
;   l_reg = l_reg * alpha + ps;
;     ...
;   PK4(p0, 0, pa0); PK4(p0, 8, pa1); PK4(p1, 0, pa2); PK4(p1, 8, pa3);
;     ...
; }
; __device__ __forceinline__ void qkt(f32x16& p0, f32x16& p1, const char* Ks, const bf16x8* qr, const f32x16& negm, int r32, int hi) {
;   p0 = negm; p1 = negm;
; #pragma unroll
;   for (int d0 = 0; d0 < 6; ++d0) { int cb = (d0 * 16 + hi * 8) * 2;
;     bf16x8 b0 = *reinterpret_cast<const bf16x8*>(Ks + KSWZ(r32, cb));
;     bf16x8 b1 = *reinterpret_cast<const bf16x8*>(Ks + KSWZ(32 + r32, cb));
;     p0 = __builtin_amdgcn_mfma_f32_32x32x16_bf16(b0, qr[d0], p0, 0, 0, 0);
;     p1 = __builtin_amdgcn_mfma_f32_32x32x16_bf16(b1, qr[d0], p1, 0, 0, 0); }
; }
; __device__ __forceinline__ void attn_unit(const bf16_t* __restrict__ Qb, const bf16_t* __restrict__ KNh, const bf16_t* __restrict__ KRb, const bf16_t* __restrict__ Vh, bf16_t* __restrict__ Ob, char* lds) {
;     ...
;     SBAR(); qkt(pA0, pA1, K_lds + ((j + 1) & 3) * SHM_K, qr, negm, r32, hi);
;     finishSM(pB0, pB1, alB, l_reg, pa0, pa1, pa2, pa3); SBAR();
;     if (j + 3 < NT) { SWRITE((j + 3) & 3, 0); } if (j + 4 < NT) { SLOAD(1, (j + 4) * KVBLK); } SBAR();
.LBB0_746:
	s_waitcnt lgkmcnt(0)
	s_barrier
	v_exp_f32_e32 v192, v96
	v_exp_f32_e32 v193, v97
	v_exp_f32_e32 v194, v98
	v_exp_f32_e32 v195, v99
	v_exp_f32_e32 v216, v100
	v_exp_f32_e32 v217, v101
	v_exp_f32_e32 v219, v102
	v_exp_f32_e32 v220, v103
	v_exp_f32_e32 v221, v104
	v_exp_f32_e32 v222, v105
	v_exp_f32_e32 v223, v106
	v_exp_f32_e32 v224, v107
	v_exp_f32_e32 v225, v108
	v_exp_f32_e32 v226, v109
	v_exp_f32_e32 v227, v110
	v_exp_f32_e32 v228, v111
	s_add_i32 s46, s89, 0xffff8000
	s_and_b32 s46, s46, 0xc000
	s_add_i32 s46, s46, 0
	s_add_i32 s46, s46, 0x10000
	v_add_u32_e32 v68, s46, v206
	ds_read_b128 v[64:67], v68
	ds_read_b128 v[184:187], v68 offset:8192
	v_add_u32_e32 v171, s46, v207
	v_exp_f32_e32 v80, v80
	v_exp_f32_e32 v81, v81
	s_waitcnt lgkmcnt(1)
	v_mfma_f32_32x32x16_bf16 v[96:111], v[64:67], v[132:135], v[32:47]
	v_exp_f32_e32 v82, v82
	v_exp_f32_e32 v83, v83
	v_exp_f32_e32 v87, v87
	v_exp_f32_e32 v229, v92
	v_exp_f32_e32 v230, v93
	v_exp_f32_e32 v231, v94
	v_exp_f32_e32 v232, v95
	s_waitcnt lgkmcnt(0)
	v_mfma_f32_32x32x16_bf16 v[64:79], v[184:187], v[132:135], v[32:47]
	ds_read_b128 v[184:187], v171
	ds_read_b128 v[188:191], v171 offset:8192
	v_add_u32_e32 v171, s46, v208
	s_waitcnt lgkmcnt(1)
	v_mfma_f32_32x32x16_bf16 v[96:111], v[184:187], v[128:131], v[96:111]
	s_waitcnt lgkmcnt(0)
	v_mfma_f32_32x32x16_bf16 v[64:79], v[188:191], v[128:131], v[64:79]
	ds_read_b128 v[184:187], v171
	ds_read_b128 v[188:191], v171 offset:8192
	v_add_u32_e32 v171, s46, v209
	s_waitcnt lgkmcnt(1)
	v_mfma_f32_32x32x16_bf16 v[96:111], v[184:187], v[124:127], v[96:111]
	s_waitcnt lgkmcnt(0)
	v_mfma_f32_32x32x16_bf16 v[64:79], v[188:191], v[124:127], v[64:79]
	ds_read_b128 v[184:187], v171
	ds_read_b128 v[188:191], v171 offset:8192
	v_add_u32_e32 v171, s46, v210
	s_waitcnt lgkmcnt(1)
	v_mfma_f32_32x32x16_bf16 v[96:111], v[184:187], v[120:123], v[96:111]
	s_waitcnt lgkmcnt(0)
	v_mfma_f32_32x32x16_bf16 v[64:79], v[188:191], v[120:123], v[64:79]
	ds_read_b128 v[184:187], v171
	ds_read_b128 v[188:191], v171 offset:8192
	v_add_u32_e32 v171, s46, v211
	s_waitcnt lgkmcnt(1)
	v_mfma_f32_32x32x16_bf16 v[96:111], v[184:187], v[116:119], v[96:111]
	s_waitcnt lgkmcnt(0)
	v_mfma_f32_32x32x16_bf16 v[64:79], v[188:191], v[116:119], v[64:79]
	ds_read_b128 v[184:187], v171
	ds_read_b128 v[188:191], v171 offset:8192
	v_cvt_pk_bf16_f32 v92, v192, v193
	v_cvt_pk_bf16_f32 v93, v194, v195
	v_cvt_pk_bf16_f32 v94, v216, v217
	v_cvt_pk_bf16_f32 v95, v219, v220
	s_waitcnt lgkmcnt(1)
	v_mfma_f32_32x32x16_bf16 v[96:111], v[184:187], v[112:115], v[96:111]
	v_exp_f32_e32 v185, v84
	v_fma_f32 v84, v165, v169, v192
	v_add_f32_e32 v84, v193, v84
	v_add_f32_e32 v84, v194, v84
	v_add_f32_e32 v84, v195, v84
	v_add_f32_e32 v84, v216, v84
	v_add_f32_e32 v84, v217, v84
	v_add_f32_e32 v84, v219, v84
	v_add_f32_e32 v84, v220, v84
	v_add_f32_e32 v84, v221, v84
	v_add_f32_e32 v84, v222, v84
	v_add_f32_e32 v84, v223, v84
	v_add_f32_e32 v84, v224, v84
	v_add_f32_e32 v84, v225, v84
	v_add_f32_e32 v84, v226, v84
	v_add_f32_e32 v84, v227, v84
	v_add_f32_e32 v84, v228, v84
	v_add_f32_e32 v84, v80, v84
	v_exp_f32_e32 v186, v85
	v_add_f32_e32 v84, v81, v84
	v_exp_f32_e32 v187, v86
	v_add_f32_e32 v84, v82, v84
	v_add_f32_e32 v84, v83, v84
	s_waitcnt lgkmcnt(0)
	v_mfma_f32_32x32x16_bf16 v[64:79], v[188:191], v[112:115], v[64:79]
	v_exp_f32_e32 v188, v88
	v_add_f32_e32 v84, v185, v84
	v_exp_f32_e32 v189, v89
	v_add_f32_e32 v84, v186, v84
	v_exp_f32_e32 v190, v90
	v_add_f32_e32 v84, v187, v84
	v_exp_f32_e32 v191, v91
	v_add_f32_e32 v84, v87, v84
	v_add_f32_e32 v84, v188, v84
	v_add_f32_e32 v84, v189, v84
	v_add_f32_e32 v84, v190, v84
	v_add_f32_e32 v84, v191, v84
	v_add_f32_e32 v84, v229, v84
	v_add_f32_e32 v84, v230, v84
	v_add_f32_e32 v84, v231, v84
	v_add_f32_e32 v152, v232, v84
	v_cvt_pk_bf16_f32 v88, v221, v222
	v_cvt_pk_bf16_f32 v89, v223, v224
	v_cvt_pk_bf16_f32 v90, v225, v226
	v_cvt_pk_bf16_f32 v91, v227, v228
	v_cvt_pk_bf16_f32 v84, v80, v81
	v_cvt_pk_bf16_f32 v85, v82, v83
	v_cvt_pk_bf16_f32 v86, v185, v186
	v_cvt_pk_bf16_f32 v87, v187, v87
	v_cvt_pk_bf16_f32 v80, v188, v189
	v_cvt_pk_bf16_f32 v81, v190, v191
	v_cvt_pk_bf16_f32 v82, v229, v230
	v_cvt_pk_bf16_f32 v83, v231, v232
	s_andn2_b64 vcc, exec, s[44:45]
	s_cbranch_vccnz .LBB0_748
	s_add_i32 s44, s48, 0
	v_add_u32_e32 v185, s48, v204
	s_add_i32 s44, s44, 0x10000
	v_add_u32_e32 v186, s44, v201
	v_add_u32_e32 v187, s44, v202
	s_waitcnt vmcnt(2)
	ds_write_b128 v185, v[136:139]
	s_waitcnt vmcnt(1)
	ds_write_b128 v186, v[140:143]
	s_waitcnt vmcnt(0)
	ds_write_b64 v187, v[172:173]

; #define ABAR() asm volatile("s_waitcnt lgkmcnt(0)\n\ts_barrier" ::: "memory")
; #define RESC(a) do { if (__any((a) < 1.f)) { if (hi == 0) al_l[r32] = (a); asm volatile("s_waitcnt lgkmcnt(0)" ::: "memory"); \
;     _Pragma("unroll") for (int d = 0; d < 2; ++d) _Pragma("unroll") for (int r = 0; r < 16; ++r) o[d][r] *= al_l[crow(r, hi)]; } } while (0)
; template <bool FIRST> __device__ __forceinline__ void partialSM(f32x16& p0, f32x16& p1, float& mref, f32x16& negm, float& alpha) {
;     ...
;   for (int r = 0; r < 16; ++r) p0[r] = __builtin_amdgcn_exp2f(p0[r]);
; __device__ __forceinline__ void attn_unit(const bf16_t* __restrict__ Qb, const bf16_t* __restrict__ KNh, const bf16_t* __restrict__ KRb, const bf16_t* __restrict__ Vh, bf16_t* __restrict__ Ob, char* lds) {
;     ...
;     pv_d0(o, vb0 + (j & 3) * SHM_V, pa0, pa1, pa2, pa3); partialSM<false>(pA0, pA1, mref, negm, alA);
;     RESC(alA); ABAR();
;   }
.LBB0_755:
	v_exp_f32_e32 v194, v96
	v_exp_f32_e32 v216, v97
	v_exp_f32_e32 v192, v98
	v_exp_f32_e32 v195, v99
	v_exp_f32_e32 v190, v100
	v_exp_f32_e32 v193, v101
	v_exp_f32_e32 v189, v102
	v_exp_f32_e32 v191, v103
	v_exp_f32_e32 v186, v104
	v_exp_f32_e32 v188, v105
	v_exp_f32_e32 v185, v106
	v_exp_f32_e32 v187, v107
	v_exp_f32_e32 v181, v108
	v_exp_f32_e32 v183, v109
	v_exp_f32_e32 v180, v110
	v_exp_f32_e32 v182, v111
	s_waitcnt lgkmcnt(0)
	s_barrier
	s_add_i32 s90, s90, 2
	s_add_i32 s89, s89, 0x8000
	s_and_b64 vcc, exec, s[42:43]
	s_cbranch_vccnz .LBB0_780
	v_mov_b32_e32 v163, v84
	s_branch .LBB0_739

; template <bool FIRST> __device__ __forceinline__ void partialSM(f32x16& p0, f32x16& p1, float& mref, f32x16& negm, float& alpha) {
;     ...
;   if (!FIRST && __builtin_expect(__all(pmax <= THRL), 1)) { alpha = 1.f; }
;   else { const float dl = FIRST ? pmax : fmaxf(pmax, 0.f); mref += dl; alpha = FIRST ? 1.f : __builtin_amdgcn_exp2f(-dl);
; #pragma unroll
;     for (int r = 0; r < 16; ++r) { p0[r] -= dl; p1[r] -= dl; }
;     const float nm = -mref;
; #pragma unroll
;     for (int r = 0; r < 16; ++r) negm[r] = nm; }
.LBB0_758:
	v_max_f32_e32 v32, v85, v85
	v_max_f32_e32 v32, 0, v32
	v_exp_f32_e64 v84, -v32
	v_add_f32_e32 v161, v161, v32
	v_xor_b32_e32 v48, 0x80000000, v161
	v_pk_add_f32 v[96:97], v[96:97], v[32:33] op_sel_hi:[1,0] neg_lo:[0,1] neg_hi:[0,1]
	v_pk_add_f32 v[98:99], v[98:99], v[32:33] op_sel_hi:[1,0] neg_lo:[0,1] neg_hi:[0,1]
	v_pk_add_f32 v[100:101], v[100:101], v[32:33] op_sel_hi:[1,0] neg_lo:[0,1] neg_hi:[0,1]
	v_pk_add_f32 v[102:103], v[102:103], v[32:33] op_sel_hi:[1,0] neg_lo:[0,1] neg_hi:[0,1]
	v_pk_add_f32 v[104:105], v[104:105], v[32:33] op_sel_hi:[1,0] neg_lo:[0,1] neg_hi:[0,1]
	v_pk_add_f32 v[106:107], v[106:107], v[32:33] op_sel_hi:[1,0] neg_lo:[0,1] neg_hi:[0,1]
	v_pk_add_f32 v[108:109], v[108:109], v[32:33] op_sel_hi:[1,0] neg_lo:[0,1] neg_hi:[0,1]
	v_pk_add_f32 v[110:111], v[110:111], v[32:33] op_sel_hi:[1,0] neg_lo:[0,1] neg_hi:[0,1]
	v_sub_f32_e32 v79, v79, v32
	v_sub_f32_e32 v78, v78, v32
	v_sub_f32_e32 v77, v77, v32
	v_sub_f32_e32 v76, v76, v32
	v_sub_f32_e32 v75, v75, v32
	v_sub_f32_e32 v74, v74, v32
	v_sub_f32_e32 v73, v73, v32
	v_sub_f32_e32 v72, v72, v32
	v_sub_f32_e32 v71, v71, v32
	v_sub_f32_e32 v70, v70, v32
	v_sub_f32_e32 v69, v69, v32
	v_sub_f32_e32 v68, v68, v32
	v_sub_f32_e32 v67, v67, v32
	v_sub_f32_e32 v66, v66, v32
	v_sub_f32_e32 v65, v65, v32
	v_sub_f32_e32 v64, v64, v32
	v_mov_b32_e32 v49, v48
	v_mov_b32_e32 v50, v48
	v_mov_b32_e32 v51, v48
	v_mov_b32_e32 v52, v48
	v_mov_b32_e32 v53, v48
	v_mov_b32_e32 v54, v48
	v_mov_b32_e32 v55, v48
	v_mov_b32_e32 v56, v48
	v_mov_b32_e32 v57, v48
	v_mov_b32_e32 v58, v48
	v_mov_b32_e32 v59, v48
	v_mov_b32_e32 v60, v48
	v_mov_b32_e32 v61, v48
	v_mov_b32_e32 v62, v48
	v_mov_b32_e32 v63, v48
	v_mov_b32_e32 v32, v48
	v_mov_b32_e32 v33, v48
	v_mov_b32_e32 v34, v48
	v_mov_b32_e32 v35, v48
	v_mov_b32_e32 v36, v48
	v_mov_b32_e32 v37, v48
	v_mov_b32_e32 v38, v48
	v_mov_b32_e32 v39, v48
	v_mov_b32_e32 v40, v48
	v_mov_b32_e32 v41, v48
	v_mov_b32_e32 v42, v48
	v_mov_b32_e32 v43, v48
	v_mov_b32_e32 v44, v48
	v_mov_b32_e32 v45, v48
	v_mov_b32_e32 v46, v48
	v_mov_b32_e32 v47, v48
	v_cmp_gt_f32_e32 vcc, 1.0, v84
	s_cbranch_vccnz .LBB0_752
	s_branch .LBB0_755
.Lf1_757:
	v_max_f32_e32 v32, v52, v52
	v_max_f32_e32 v32, 0, v32
	v_exp_f32_e64 v169, -v32
	v_add_f32_e32 v161, v161, v32
	v_xor_b32_e32 v48, 0x80000000, v161
	v_pk_add_f32 v[96:97], v[96:97], v[32:33] op_sel_hi:[1,0] neg_lo:[0,1] neg_hi:[0,1]
	v_pk_add_f32 v[98:99], v[98:99], v[32:33] op_sel_hi:[1,0] neg_lo:[0,1] neg_hi:[0,1]
	v_pk_add_f32 v[100:101], v[100:101], v[32:33] op_sel_hi:[1,0] neg_lo:[0,1] neg_hi:[0,1]
	v_pk_add_f32 v[102:103], v[102:103], v[32:33] op_sel_hi:[1,0] neg_lo:[0,1] neg_hi:[0,1]
	v_pk_add_f32 v[104:105], v[104:105], v[32:33] op_sel_hi:[1,0] neg_lo:[0,1] neg_hi:[0,1]
	v_pk_add_f32 v[106:107], v[106:107], v[32:33] op_sel_hi:[1,0] neg_lo:[0,1] neg_hi:[0,1]
	v_pk_add_f32 v[108:109], v[108:109], v[32:33] op_sel_hi:[1,0] neg_lo:[0,1] neg_hi:[0,1]
	v_pk_add_f32 v[110:111], v[110:111], v[32:33] op_sel_hi:[1,0] neg_lo:[0,1] neg_hi:[0,1]
	v_sub_f32_e32 v95, v95, v32
	v_sub_f32_e32 v94, v94, v32
	v_sub_f32_e32 v93, v93, v32
	v_sub_f32_e32 v92, v92, v32
	v_sub_f32_e32 v91, v91, v32
	v_sub_f32_e32 v90, v90, v32
	v_sub_f32_e32 v89, v89, v32
	v_sub_f32_e32 v88, v88, v32
	v_sub_f32_e32 v87, v87, v32
	v_sub_f32_e32 v86, v86, v32
	v_sub_f32_e32 v85, v85, v32
	v_sub_f32_e32 v84, v84, v32
	v_sub_f32_e32 v83, v83, v32
	v_sub_f32_e32 v82, v82, v32
	v_sub_f32_e32 v81, v81, v32
	v_sub_f32_e32 v80, v80, v32
	v_mov_b32_e32 v49, v48
	v_mov_b32_e32 v50, v48
	v_mov_b32_e32 v51, v48
	v_mov_b32_e32 v52, v48
	v_mov_b32_e32 v53, v48
	v_mov_b32_e32 v54, v48
	v_mov_b32_e32 v55, v48
	v_mov_b32_e32 v56, v48
	v_mov_b32_e32 v57, v48
	v_mov_b32_e32 v58, v48
	v_mov_b32_e32 v59, v48
	v_mov_b32_e32 v60, v48
	v_mov_b32_e32 v61, v48
	v_mov_b32_e32 v62, v48
	v_mov_b32_e32 v63, v48
	v_mov_b32_e32 v32, v48
	v_mov_b32_e32 v33, v48
	v_mov_b32_e32 v34, v48
	v_mov_b32_e32 v35, v48
	v_mov_b32_e32 v36, v48
	v_mov_b32_e32 v37, v48
	v_mov_b32_e32 v38, v48
	v_mov_b32_e32 v39, v48
	v_mov_b32_e32 v40, v48
	v_mov_b32_e32 v41, v48
	v_mov_b32_e32 v42, v48
	v_mov_b32_e32 v43, v48
	v_mov_b32_e32 v44, v48
	v_mov_b32_e32 v45, v48
	v_mov_b32_e32 v46, v48
	v_mov_b32_e32 v47, v48
	v_cmp_gt_f32_e32 vcc, 1.0, v169
	s_cbranch_vccnz .Lf1_743
	s_branch .Lf1_746
; template <bool FIRST> __device__ __forceinline__ void partialSM(f32x16& p0, f32x16& p1, float& mref, f32x16& negm, float& alpha) {
;     ...
;   if (!FIRST && __builtin_expect(__all(pmax <= THRL), 1)) { alpha = 1.f; }
;   else { const float dl = FIRST ? pmax : fmaxf(pmax, 0.f); mref += dl; alpha = FIRST ? 1.f : __builtin_amdgcn_exp2f(-dl);
; #pragma unroll
;     for (int r = 0; r < 16; ++r) { p0[r] -= dl; p1[r] -= dl; }
;     const float nm = -mref;
; #pragma unroll
;     for (int r = 0; r < 16; ++r) negm[r] = nm; }
.Lf1_758:
	v_max_f32_e32 v32, v85, v85
	v_max_f32_e32 v32, 0, v32
	v_exp_f32_e64 v84, -v32
	v_add_f32_e32 v161, v161, v32
	v_xor_b32_e32 v48, 0x80000000, v161
	v_pk_add_f32 v[96:97], v[96:97], v[32:33] op_sel_hi:[1,0] neg_lo:[0,1] neg_hi:[0,1]
	v_pk_add_f32 v[98:99], v[98:99], v[32:33] op_sel_hi:[1,0] neg_lo:[0,1] neg_hi:[0,1]
	v_pk_add_f32 v[100:101], v[100:101], v[32:33] op_sel_hi:[1,0] neg_lo:[0,1] neg_hi:[0,1]
	v_pk_add_f32 v[102:103], v[102:103], v[32:33] op_sel_hi:[1,0] neg_lo:[0,1] neg_hi:[0,1]
	v_pk_add_f32 v[104:105], v[104:105], v[32:33] op_sel_hi:[1,0] neg_lo:[0,1] neg_hi:[0,1]
	v_pk_add_f32 v[106:107], v[106:107], v[32:33] op_sel_hi:[1,0] neg_lo:[0,1] neg_hi:[0,1]
	v_pk_add_f32 v[108:109], v[108:109], v[32:33] op_sel_hi:[1,0] neg_lo:[0,1] neg_hi:[0,1]
	v_pk_add_f32 v[110:111], v[110:111], v[32:33] op_sel_hi:[1,0] neg_lo:[0,1] neg_hi:[0,1]
	v_sub_f32_e32 v79, v79, v32
	v_sub_f32_e32 v78, v78, v32
	v_sub_f32_e32 v77, v77, v32
	v_sub_f32_e32 v76, v76, v32
	v_sub_f32_e32 v75, v75, v32
	v_sub_f32_e32 v74, v74, v32
	v_sub_f32_e32 v73, v73, v32
	v_sub_f32_e32 v72, v72, v32
	v_sub_f32_e32 v71, v71, v32
	v_sub_f32_e32 v70, v70, v32
	v_sub_f32_e32 v69, v69, v32
	v_sub_f32_e32 v68, v68, v32
	v_sub_f32_e32 v67, v67, v32
	v_sub_f32_e32 v66, v66, v32
	v_sub_f32_e32 v65, v65, v32
	v_sub_f32_e32 v64, v64, v32
	v_mov_b32_e32 v49, v48
	v_mov_b32_e32 v50, v48
	v_mov_b32_e32 v51, v48
	v_mov_b32_e32 v52, v48
	v_mov_b32_e32 v53, v48
	v_mov_b32_e32 v54, v48
	v_mov_b32_e32 v55, v48
	v_mov_b32_e32 v56, v48
	v_mov_b32_e32 v57, v48
	v_mov_b32_e32 v58, v48
	v_mov_b32_e32 v59, v48
	v_mov_b32_e32 v60, v48
	v_mov_b32_e32 v61, v48
	v_mov_b32_e32 v62, v48
	v_mov_b32_e32 v63, v48
	v_mov_b32_e32 v32, v48
	v_mov_b32_e32 v33, v48
	v_mov_b32_e32 v34, v48
	v_mov_b32_e32 v35, v48
	v_mov_b32_e32 v36, v48
	v_mov_b32_e32 v37, v48
	v_mov_b32_e32 v38, v48
	v_mov_b32_e32 v39, v48
	v_mov_b32_e32 v40, v48
	v_mov_b32_e32 v41, v48
	v_mov_b32_e32 v42, v48
	v_mov_b32_e32 v43, v48
	v_mov_b32_e32 v44, v48
	v_mov_b32_e32 v45, v48
	v_mov_b32_e32 v46, v48
	v_mov_b32_e32 v47, v48
	v_cmp_gt_f32_e32 vcc, 1.0, v84
	s_cbranch_vccnz .Lf1_752
	s_branch .Lf1_755
.Lf2_757:
	v_max_f32_e32 v32, v52, v52
	v_max_f32_e32 v32, 0, v32
	v_exp_f32_e64 v169, -v32
	v_add_f32_e32 v161, v161, v32
	v_xor_b32_e32 v48, 0x80000000, v161
	v_pk_add_f32 v[96:97], v[96:97], v[32:33] op_sel_hi:[1,0] neg_lo:[0,1] neg_hi:[0,1]
	v_pk_add_f32 v[98:99], v[98:99], v[32:33] op_sel_hi:[1,0] neg_lo:[0,1] neg_hi:[0,1]
	v_pk_add_f32 v[100:101], v[100:101], v[32:33] op_sel_hi:[1,0] neg_lo:[0,1] neg_hi:[0,1]
	v_pk_add_f32 v[102:103], v[102:103], v[32:33] op_sel_hi:[1,0] neg_lo:[0,1] neg_hi:[0,1]
	v_pk_add_f32 v[104:105], v[104:105], v[32:33] op_sel_hi:[1,0] neg_lo:[0,1] neg_hi:[0,1]
	v_pk_add_f32 v[106:107], v[106:107], v[32:33] op_sel_hi:[1,0] neg_lo:[0,1] neg_hi:[0,1]
	v_pk_add_f32 v[108:109], v[108:109], v[32:33] op_sel_hi:[1,0] neg_lo:[0,1] neg_hi:[0,1]
	v_pk_add_f32 v[110:111], v[110:111], v[32:33] op_sel_hi:[1,0] neg_lo:[0,1] neg_hi:[0,1]
	v_sub_f32_e32 v95, v95, v32
	v_sub_f32_e32 v94, v94, v32
	v_sub_f32_e32 v93, v93, v32
	v_sub_f32_e32 v92, v92, v32
	v_sub_f32_e32 v91, v91, v32
	v_sub_f32_e32 v90, v90, v32
	v_sub_f32_e32 v89, v89, v32
	v_sub_f32_e32 v88, v88, v32
	v_sub_f32_e32 v87, v87, v32
	v_sub_f32_e32 v86, v86, v32
	v_sub_f32_e32 v85, v85, v32
	v_sub_f32_e32 v84, v84, v32
	v_sub_f32_e32 v83, v83, v32
	v_sub_f32_e32 v82, v82, v32
	v_sub_f32_e32 v81, v81, v32
	v_sub_f32_e32 v80, v80, v32
	v_mov_b32_e32 v49, v48
	v_mov_b32_e32 v50, v48
	v_mov_b32_e32 v51, v48
	v_mov_b32_e32 v52, v48
	v_mov_b32_e32 v53, v48
	v_mov_b32_e32 v54, v48
	v_mov_b32_e32 v55, v48
	v_mov_b32_e32 v56, v48
	v_mov_b32_e32 v57, v48
	v_mov_b32_e32 v58, v48
	v_mov_b32_e32 v59, v48
	v_mov_b32_e32 v60, v48
	v_mov_b32_e32 v61, v48
	v_mov_b32_e32 v62, v48
	v_mov_b32_e32 v63, v48
	v_mov_b32_e32 v32, v48
	v_mov_b32_e32 v33, v48
	v_mov_b32_e32 v34, v48
	v_mov_b32_e32 v35, v48
	v_mov_b32_e32 v36, v48
	v_mov_b32_e32 v37, v48
	v_mov_b32_e32 v38, v48
	v_mov_b32_e32 v39, v48
	v_mov_b32_e32 v40, v48
	v_mov_b32_e32 v41, v48
	v_mov_b32_e32 v42, v48
	v_mov_b32_e32 v43, v48
	v_mov_b32_e32 v44, v48
	v_mov_b32_e32 v45, v48
	v_mov_b32_e32 v46, v48
	v_mov_b32_e32 v47, v48
	v_cmp_gt_f32_e32 vcc, 1.0, v169
	s_cbranch_vccnz .Lf2_743
	s_branch .Lf2_746

; #define SBAR() __builtin_amdgcn_sched_barrier(0)
; #define RESC(a) do { if (__any((a) < 1.f)) { if (hi == 0) al_l[r32] = (a); asm volatile("s_waitcnt lgkmcnt(0)" ::: "memory"); \
;     _Pragma("unroll") for (int d = 0; d < 2; ++d) _Pragma("unroll") for (int r = 0; r < 16; ++r) o[d][r] *= al_l[crow(r, hi)]; } } while (0)
; __device__ __forceinline__ void attn_unit(const bf16_t* __restrict__ Qb, const bf16_t* __restrict__ KNh, const bf16_t* __restrict__ KRb, const bf16_t* __restrict__ Vh, bf16_t* __restrict__ Ob, char* lds) {
;     ...
;   SBAR(); qkt(pB0, pB1, K_lds + ((NT - 1) & 3) * SHM_K, qr, negm, r32, hi);
;   finishSM(pA0, pA1, alA, l_reg, pa0, pa1, pa2, pa3); SBAR();
;   pv_d0(o, vb0 + ((NT - 2) & 3) * SHM_V, pa0, pa1, pa2, pa3); partialSM<false>(pB0, pB1, mref, negm, alB);
;   RESC(alB);
;   finishSM(pB0, pB1, alB, l_reg, pa0, pa1, pa2, pa3); SBAR();
;   pv_d0(o, vb0 + ((NT - 1) & 3) * SHM_V, pa0, pa1, pa2, pa3);
.LBB0_780:
	v_mov_b32_e32 v243, v152
	s_nop 1
	v_permlane32_swap_b32_e32 v152, v243
	v_add_f32_e32 v152, v152, v243
	v_mov_b64_e32 v[48:49], v[32:33]
	v_mov_b64_e32 v[50:51], v[34:35]
	v_mov_b64_e32 v[52:53], v[36:37]
	v_mov_b64_e32 v[54:55], v[38:39]
	v_mov_b64_e32 v[56:57], v[40:41]
	v_mov_b64_e32 v[58:59], v[42:43]
	v_mov_b64_e32 v[60:61], v[44:45]
	v_mov_b64_e32 v[62:63], v[46:47]
	s_add_i32 s41, 0, 0x1c000
	v_add_u32_e32 v32, s41, v206
	ds_read_b128 v[80:83], v32
	ds_read_b128 v[86:89], v32 offset:8192
	v_add_u32_e32 v85, s41, v207
	v_add_u32_e32 v98, s41, v208
	v_add_u32_e32 v102, s41, v209
	s_waitcnt lgkmcnt(1)
	v_mfma_f32_32x32x16_bf16 v[32:47], v[80:83], v[132:135], v[48:63]
	ds_read_b128 v[80:83], v85
	ds_read_b128 v[90:93], v85 offset:8192
	ds_read_b128 v[94:97], v98
	ds_read_b128 v[98:101], v98 offset:8192
	v_add_u32_e32 v85, s41, v210
	v_exp_f32_e32 v110, v69
	v_exp_f32_e32 v111, v70
	s_waitcnt lgkmcnt(4)
	v_mfma_f32_32x32x16_bf16 v[48:63], v[86:89], v[132:135], v[48:63]
	ds_read_b128 v[86:89], v102
	ds_read_b128 v[102:105], v102 offset:8192
	ds_read_b128 v[106:109], v85
	ds_read_b128 v[132:135], v85 offset:8192
	v_add_u32_e32 v85, s41, v211
	s_waitcnt vmcnt(2)
	ds_read_b128 v[136:139], v85
	s_waitcnt vmcnt(1)
	ds_read_b128 v[140:143], v85 offset:8192
	v_exp_f32_e32 v85, v68
	s_waitcnt lgkmcnt(9)
	v_mfma_f32_32x32x16_bf16 v[32:47], v[80:83], v[128:131], v[32:47]
	v_exp_f32_e32 v80, v64
	v_add_f32_e32 v64, 0, v194
	v_add_f32_e32 v64, v216, v64
	v_add_f32_e32 v64, v192, v64
	v_add_f32_e32 v64, v195, v64
	v_add_f32_e32 v64, v190, v64
	v_add_f32_e32 v64, v193, v64
	s_waitcnt lgkmcnt(8)
	v_mfma_f32_32x32x16_bf16 v[48:63], v[90:93], v[128:131], v[48:63]
	v_add_f32_e32 v64, v189, v64
	v_add_f32_e32 v64, v191, v64
	v_add_f32_e32 v64, v186, v64
	v_add_f32_e32 v64, v188, v64
	v_add_f32_e32 v64, v185, v64
	v_add_f32_e32 v64, v187, v64
	v_add_f32_e32 v64, v181, v64
	s_waitcnt lgkmcnt(7)
	v_mfma_f32_32x32x16_bf16 v[32:47], v[94:97], v[124:127], v[32:47]
	v_exp_f32_e32 v81, v65
	v_add_f32_e32 v64, v183, v64
	v_exp_f32_e32 v82, v66
	v_add_f32_e32 v64, v180, v64
	v_exp_f32_e32 v83, v67
	v_add_f32_e32 v64, v182, v64
	v_add_f32_e32 v64, v80, v64
	s_waitcnt lgkmcnt(6)
	v_mfma_f32_32x32x16_bf16 v[48:63], v[98:101], v[124:127], v[48:63]
	v_add_f32_e32 v64, v81, v64
	v_add_f32_e32 v64, v82, v64
	v_exp_f32_e32 v90, v71
	v_add_f32_e32 v64, v83, v64
	v_exp_f32_e32 v91, v72
	v_add_f32_e32 v64, v85, v64
	v_exp_f32_e32 v92, v73
	s_waitcnt lgkmcnt(5)
	v_mfma_f32_32x32x16_bf16 v[32:47], v[86:89], v[120:123], v[32:47]
	v_add_f32_e32 v64, v110, v64
	v_exp_f32_e32 v93, v74
	v_add_f32_e32 v64, v111, v64
	v_exp_f32_e32 v128, v75
	v_add_f32_e32 v64, v90, v64
	v_exp_f32_e32 v129, v76
	v_add_f32_e32 v64, v91, v64
	s_waitcnt lgkmcnt(4)
	v_mfma_f32_32x32x16_bf16 v[48:63], v[102:105], v[120:123], v[48:63]
	v_exp_f32_e32 v130, v77
	v_add_f32_e32 v64, v92, v64
	v_exp_f32_e32 v94, v78
	v_add_f32_e32 v64, v93, v64
	v_exp_f32_e32 v95, v79
	v_add_f32_e32 v64, v128, v64
	v_add_f32_e32 v64, v129, v64
	s_waitcnt lgkmcnt(3)
	v_mfma_f32_32x32x16_bf16 v[32:47], v[106:109], v[116:119], v[32:47]
	v_add_f32_e32 v64, v130, v64
	v_add_f32_e32 v64, v94, v64
	v_add_f32_e32 v64, v95, v64
	v_mov_b32_e32 v65, v64
	s_nop 1
	v_permlane32_swap_b32_e32 v64, v65
	v_cvt_pk_bf16_f32 v66, v194, v216
	s_waitcnt lgkmcnt(2)
	v_mfma_f32_32x32x16_bf16 v[48:63], v[132:135], v[116:119], v[48:63]
	v_cvt_pk_bf16_f32 v67, v192, v195
	v_cvt_pk_bf16_f32 v68, v190, v193
	v_cvt_pk_bf16_f32 v69, v189, v191
	v_cvt_pk_bf16_f32 v70, v186, v188
	v_cvt_pk_bf16_f32 v71, v185, v187
	v_cvt_pk_bf16_f32 v72, v181, v183
	v_cvt_pk_bf16_f32 v73, v180, v182
	s_waitcnt lgkmcnt(1)
	v_mfma_f32_32x32x16_bf16 v[32:47], v[136:139], v[112:115], v[32:47]
	v_cvt_pk_bf16_f32 v74, v80, v81
	v_cvt_pk_bf16_f32 v75, v82, v83
	v_cvt_pk_bf16_f32 v76, v85, v110
	v_cvt_pk_bf16_f32 v77, v111, v90
	v_cvt_pk_bf16_f32 v78, v91, v92
	v_cvt_pk_bf16_f32 v79, v93, v128
	v_cvt_pk_bf16_f32 v80, v129, v130
	s_waitcnt lgkmcnt(0)
	v_mfma_f32_32x32x16_bf16 v[48:63], v[140:143], v[112:115], v[48:63]
	v_cvt_pk_bf16_f32 v81, v94, v95
	ds_read_b64_tr_b16 v[86:87], v203 offset:32768
	ds_read_b64_tr_b16 v[88:89], v203 offset:34816
	ds_read_b64_tr_b16 v[92:93], v203 offset:35328
	ds_read_b64_tr_b16 v[90:91], v203 offset:33280
	s_nop 5
	v_max_f32_e32 v82, v33, v33
	v_max_f32_e32 v83, v32, v32
	s_waitcnt lgkmcnt(2)
	v_mfma_f32_32x32x16_bf16 v[0:15], v[66:69], v[86:89], v[0:15]
	ds_read_b64_tr_b16 v[86:87], v203 offset:36864
	ds_read_b64_tr_b16 v[88:89], v203 offset:38912
	ds_read_b64_tr_b16 v[96:97], v203 offset:39424
	ds_read_b64_tr_b16 v[94:95], v203 offset:37376
	v_max_f32_e32 v82, v83, v82
	v_max3_f32 v82, v82, v34, v35
	v_max3_f32 v82, v82, v36, v37
	s_waitcnt lgkmcnt(4)
	v_mfma_f32_32x32x16_bf16 v[16:31], v[66:69], v[90:93], v[16:31]
	v_max3_f32 v66, v82, v38, v39
	v_max3_f32 v66, v66, v40, v41
	v_max3_f32 v66, v66, v42, v43
	v_max3_f32 v66, v66, v44, v45
	v_max3_f32 v66, v66, v46, v47
	v_max3_f32 v66, v66, v48, v49
	v_max3_f32 v66, v66, v50, v51
	s_waitcnt lgkmcnt(2)
	v_mfma_f32_32x32x16_bf16 v[0:15], v[70:73], v[86:89], v[0:15]
	ds_read_b64_tr_b16 v[86:87], v203 offset:40960
	ds_read_b64_tr_b16 v[88:89], v203 offset:43008
	ds_read_b64_tr_b16 v[100:101], v203 offset:43520
	ds_read_b64_tr_b16 v[98:99], v203 offset:41472
	v_max3_f32 v66, v66, v52, v53
	v_max3_f32 v66, v66, v54, v55
	v_max3_f32 v66, v66, v56, v57
	v_max3_f32 v66, v66, v58, v59
	v_max3_f32 v66, v66, v60, v61
	v_max3_f32 v66, v66, v62, v63
	s_waitcnt lgkmcnt(4)
	v_mfma_f32_32x32x16_bf16 v[16:31], v[70:73], v[94:97], v[16:31]
	v_mov_b32_e32 v67, v66
	s_nop 1
	v_permlane32_swap_b32_e32 v66, v67
	v_max_f32_e32 v67, v67, v67
	v_max_f32_e32 v66, v66, v66
	v_max_f32_e32 v67, v66, v67
	v_cmp_ge_f32_e32 vcc, s86, v67
	s_waitcnt lgkmcnt(2)
	v_mfma_f32_32x32x16_bf16 v[0:15], v[74:77], v[86:89], v[0:15]
	ds_read_b64_tr_b16 v[86:87], v203 offset:45056
	ds_read_b64_tr_b16 v[88:89], v203 offset:47104
	ds_read_b64_tr_b16 v[104:105], v203 offset:47616
	ds_read_b64_tr_b16 v[102:103], v203 offset:45568
	s_cmp_eq_u64 vcc, exec
	v_mov_b32_e32 v66, 1.0
	s_waitcnt lgkmcnt(4)
	v_mfma_f32_32x32x16_bf16 v[16:31], v[74:77], v[98:101], v[16:31]
	s_waitcnt lgkmcnt(2)
	v_mfma_f32_32x32x16_bf16 v[0:15], v[78:81], v[86:89], v[0:15]
	s_waitcnt lgkmcnt(0)
	v_mfma_f32_32x32x16_bf16 v[16:31], v[78:81], v[102:105], v[16:31]
	s_cbranch_scc0 .LBB0_787
	v_cmp_gt_f32_e32 vcc, 1.0, v66
	s_cbranch_vccz .LBB0_785
